# o32 plus nt cache hint on out-proj epilogue stores (both layers)
# baseline (speedup 1.0000x reference)
; #define PG8_LAS __attribute__((address_space(3)))
; __device__ __forceinline__ u32x4 pack8(const f32x4& a, const f32x4& b) { u32x4 w; w.x = cvt_pk_bf16(a[0], a[1]); w.y = cvt_pk_bf16(a[2], a[3]); w.z = cvt_pk_bf16(b[0], b[1]); w.w = cvt_pk_bf16(b[2], b[3]); return w; }
; __device__ __forceinline__ float hsq4(const f32x4& a) { return (a[0] * a[0] + a[1] * a[1]) + (a[2] * a[2] + a[3] * a[3]); }
; #define PG8_FENCE() asm volatile("" ::: "memory")
;     __device__ __forceinline__ void operator()(const f32x4 (&acc)[2][2][4][2], const Unit& u, int wr, int wc, int fr, int fq) const {
;     ...
;         if (MIDS) { PG8_LAS const unsigned char* sp = slds + RSTAT_OFF + (u.ui & 1) * 2048 + (wr * 64 + fr) * 8 + 4;
; #pragma unroll
;             for (int ai = 0; ai < 2; ++ai)
; #pragma unroll
;                 for (int m = 0; m < 4; ++m) rs[ai][m] = *(PG8_LAS const float*)(sp + (ai * 128 + m * 16) * 8);
;             PG8_FENCE(); }
; #pragma unroll
;         for (int bj = 0; bj < 2; ++bj) { const int cb = c0 + bj * HALF;
;             const f32x4 g0 = ldb<f32x4>(gate, (unsigned)((b * NMOD + cb) * 4)), g1 = ldb<f32x4>(gate, (unsigned)((b * NMOD + cb + 4) * 4));
;             f32x4 m0 = (f32x4){0.f, 0.f, 0.f, 0.f}, m1 = m0; if (gm) { m0 = ldb<f32x4>(gm, (unsigned)((b * DM + cb) * 4)); m1 = ldb<f32x4>(gm, (unsigned)((b * DM + cb + 4) * 4)); }
;             if (XF32) {
; #pragma unroll
;                 for (int ai = 0; ai < 2; ++ai) {
;                     f32x4 xv[4][2];
; #pragma unroll
;                     for (int m = 0; m < 4; ++m) { const unsigned off = (unsigned)((PG8_ROW(u, ai, m) * DM + cb) * 4); xv[m][0] = ldb<f32x4>(xin, off); xv[m][1] = ldb<f32x4>(xin, off + 16); }
;                     PG8_FENCE();
; #pragma unroll
;                     for (int m = 0; m < 4; ++m) { const unsigned off = (unsigned)((PG8_ROW(u, ai, m) * DM + cb) * 2), offx = (unsigned)(PG8_ROW(u, ai, m) * (DM * 4) + DM * 2 + cb * 2);
;                         const f32x4 x0 = xv[m][0] + g0 * (acc[ai][bj][m][0] * rs[ai][m]), x1 = xv[m][1] + g1 * (acc[ai][bj][m][1] * rs[ai][m]);
;                         stb(xout, offx, pack8(x0, x1));
;                         if (gm) { ss[ai][m] += hsq4(x0) + hsq4(x1); stb(A, off, pack8(x0 * m0, x1 * m1)); } }
.LBB13_948:
	v_mbcnt_lo_u32_b32 v9, -1, 0
	v_mbcnt_hi_u32_b32 v9, -1, v9
	s_lshl_b32 s29, s34, 8
	v_and_or_b32 v175, v9, 15, s57
	v_ashrrev_i32_e32 v11, 1, v9
	v_lshlrev_b32_e32 v10, 3, v175
	v_add3_u32 v10, 0, v140, v10
	s_ashr_i32 s31, s12, 3
	v_and_b32_e32 v11, -8, v11
	s_or_b32 s29, s29, s58
	v_add_u32_e32 v140, 0x21804, v10
	v_add_u32_e32 v141, 0x21884, v10
	v_add_u32_e32 v142, 0x21904, v10
	v_add_u32_e32 v143, 0x21984, v10
	v_add_u32_e32 v144, 0x21c04, v10
	v_add_u32_e32 v145, 0x21c84, v10
	v_add_u32_e32 v146, 0x21d04, v10
	v_add_u32_e32 v10, 0x21d84, v10
	v_add_u32_e32 v169, s29, v11
	s_mul_i32 s29, s31, 0x1800
	s_lshl_b32 s35, s12, 20
	ds_read_b32 v186, v140
	ds_read_b32 v184, v141
	ds_read_b32 v174, v142
	ds_read_b32 v172, v143
	ds_read_b32 v170, v144
	ds_read_b32 v168, v145
	ds_read_b32 v166, v146
	ds_read_b32 v10, v10
	v_add_lshl_u32 v11, v169, s29, 2
	v_lshlrev_b32_e32 v189, 2, v169
	v_lshl_add_u32 v171, v175, 12, s35
	global_load_dwordx4 v[148:151], v11, s[16:17] offset:16
	global_load_dwordx4 v[152:155], v11, s[16:17]
	v_add_u32_e32 v11, v189, v171
	global_load_dwordx4 v[176:179], v11, s[2:3]
	global_load_dwordx4 v[190:193], v11, s[2:3] offset:16
	v_or_b32_e32 v11, 0x10000, v171
	s_lshl_b32 s31, s31, 12
	v_add_u32_e32 v173, v11, v189
	v_add_u32_e32 v140, s31, v189
	global_load_dwordx4 v[194:197], v173, s[2:3]
	global_load_dwordx4 v[144:147], v140, s[18:19]
	s_nop 0
	global_load_dwordx4 v[140:143], v140, s[18:19] offset:16
	s_nop 0
	global_load_dwordx4 v[198:201], v173, s[2:3] offset:16
	v_or_b32_e32 v173, 0x20000, v171
	v_add_u32_e32 v180, v173, v189
	global_load_dwordx4 v[202:205], v180, s[2:3]
	global_load_dwordx4 v[206:209], v180, s[2:3] offset:16
	v_or_b32_e32 v188, 0x30000, v171
	v_add_u32_e32 v180, v188, v189
	global_load_dwordx4 v[210:213], v180, s[2:3] offset:16
	global_load_dwordx4 v[214:217], v180, s[2:3]
	v_lshl_add_u32 v230, s12, 8, v175
	v_add_u32_e32 v220, 16, v230
	v_lshlrev_b32_e32 v231, 1, v169
	v_lshlrev_b32_e32 v187, 12, v220
	v_lshlrev_b32_e32 v175, 12, v230
	v_add_u32_e32 v232, 0x800, v231
	s_waitcnt lgkmcnt(0)
	v_pk_mul_f32 v[136:137], v[136:137], v[186:187] op_sel_hi:[1,0]
	v_pk_mul_f32 v[138:139], v[138:139], v[186:187] op_sel_hi:[1,0]
	v_pk_mul_f32 v[132:133], v[132:133], v[186:187] op_sel_hi:[1,0]
	v_lshlrev_b32_e32 v185, 11, v230
	v_add_u32_e32 v222, v232, v175
	v_pk_mul_f32 v[134:135], v[134:135], v[186:187] op_sel_hi:[1,0]
	v_add_u32_e32 v221, v231, v185
	v_pk_mul_f32 v[218:219], v[128:129], v[184:185] op_sel_hi:[1,0]
	v_pk_mul_f32 v[128:129], v[130:131], v[184:185] op_sel_hi:[1,0]
	v_add_u32_e32 v223, v232, v187
	v_pk_mul_f32 v[88:89], v[88:89], v[166:167] op_sel_hi:[1,0]
	v_pk_mul_f32 v[90:91], v[90:91], v[166:167] op_sel_hi:[1,0]
	v_pk_mul_f32 v[84:85], v[84:85], v[166:167] op_sel_hi:[1,0]
	v_pk_mul_f32 v[86:87], v[86:87], v[166:167] op_sel_hi:[1,0]
	v_pk_mul_f32 v[80:81], v[80:81], v[10:11] op_sel_hi:[1,0]
	v_pk_mul_f32 v[82:83], v[82:83], v[10:11] op_sel_hi:[1,0]
	v_pk_mul_f32 v[76:77], v[76:77], v[10:11] op_sel_hi:[1,0]
	v_pk_mul_f32 v[78:79], v[78:79], v[10:11] op_sel_hi:[1,0]
	v_cmp_gt_u32_e32 vcc, 16, v9
	v_add_u32_e32 v9, s57, v9
	s_waitcnt vmcnt(0)
	v_pk_fma_f32 v[178:179], v[138:139], v[154:155], v[178:179]
	v_pk_fma_f32 v[182:183], v[136:137], v[152:153], v[176:177]
	v_pk_fma_f32 v[180:181], v[132:133], v[148:149], v[190:191]
	v_cvt_pk_bf16_f32 v132, v182, v183
	v_cvt_pk_bf16_f32 v133, v178, v179
	v_pk_fma_f32 v[176:177], v[134:135], v[150:151], v[192:193]
	v_cvt_pk_bf16_f32 v134, v180, v181
	v_pk_mul_f32 v[136:137], v[146:147], v[178:179]
	v_cvt_pk_bf16_f32 v135, v176, v177
	v_pk_mul_f32 v[138:139], v[144:145], v[182:183]
	global_store_dwordx4 v222, v[132:135], s[8:9] nt
	v_pk_mul_f32 v[190:191], v[142:143], v[176:177]
	v_pk_mul_f32 v[192:193], v[140:141], v[180:181]
	v_cvt_pk_bf16_f32 v132, v138, v139
	v_cvt_pk_bf16_f32 v133, v136, v137
	v_pk_fma_f32 v[128:129], v[128:129], v[154:155], v[196:197]
	v_cvt_pk_bf16_f32 v134, v192, v193
	v_cvt_pk_bf16_f32 v135, v190, v191
	global_store_dwordx4 v221, v[132:135], s[20:21] nt
	v_pk_fma_f32 v[130:131], v[218:219], v[152:153], v[194:195]
	v_lshlrev_b32_e32 v195, 11, v220
	v_pk_mul_f32 v[132:133], v[124:125], v[184:185] op_sel_hi:[1,0]
	v_pk_mul_f32 v[124:125], v[126:127], v[184:185] op_sel_hi:[1,0]
	v_pk_fma_f32 v[126:127], v[132:133], v[148:149], v[198:199]
	v_cvt_pk_bf16_f32 v132, v130, v131
	v_cvt_pk_bf16_f32 v133, v128, v129
	v_pk_fma_f32 v[124:125], v[124:125], v[150:151], v[200:201]
	v_cvt_pk_bf16_f32 v134, v126, v127
	v_add_u32_e32 v190, v195, v231
	v_cvt_pk_bf16_f32 v135, v124, v125
	global_store_dwordx4 v223, v[132:135], s[8:9] nt
	v_pk_mul_f32 v[136:137], v[142:143], v[124:125]
	v_pk_mul_f32 v[138:139], v[140:141], v[126:127]
	v_pk_mul_f32 v[132:133], v[144:145], v[130:131]
	v_pk_mul_f32 v[134:135], v[146:147], v[128:129]
	v_cvt_pk_bf16_f32 v132, v132, v133
	v_add_u32_e32 v191, 0x80, v230
	v_cvt_pk_bf16_f32 v133, v134, v135
	v_cvt_pk_bf16_f32 v134, v138, v139
	v_cvt_pk_bf16_f32 v135, v136, v137
	global_store_dwordx4 v190, v[132:135], s[20:21] nt
	v_add_u32_e32 v136, 32, v230
	v_lshlrev_b32_e32 v197, 12, v136
	v_pk_mul_f32 v[132:133], v[120:121], v[174:175] op_sel_hi:[1,0]
	v_pk_mul_f32 v[120:121], v[122:123], v[174:175] op_sel_hi:[1,0]
	v_pk_fma_f32 v[122:123], v[132:133], v[152:153], v[202:203]
	v_pk_mul_f32 v[132:133], v[116:117], v[174:175] op_sel_hi:[1,0]
	v_add_u32_e32 v137, v232, v197
	v_pk_fma_f32 v[120:121], v[120:121], v[154:155], v[204:205]
	v_pk_mul_f32 v[116:117], v[118:119], v[174:175] op_sel_hi:[1,0]
	v_pk_fma_f32 v[118:119], v[132:133], v[148:149], v[206:207]
	v_cvt_pk_bf16_f32 v132, v122, v123
; __device__ __forceinline__ u32x4 pack8(const f32x4& a, const f32x4& b) { u32x4 w; w.x = cvt_pk_bf16(a[0], a[1]); w.y = cvt_pk_bf16(a[2], a[3]); w.z = cvt_pk_bf16(b[0], b[1]); w.w = cvt_pk_bf16(b[2], b[3]); return w; }
; __device__ __forceinline__ float hsq4(const f32x4& a) { return (a[0] * a[0] + a[1] * a[1]) + (a[2] * a[2] + a[3] * a[3]); }
; #define PG8_FENCE() asm volatile("" ::: "memory")
;     __device__ __forceinline__ void operator()(const f32x4 (&acc)[2][2][4][2], const Unit& u, int wr, int wc, int fr, int fq) const {
;     ...
;                 for (int ai = 0; ai < 2; ++ai) {
;                     f32x4 xv[4][2];
; #pragma unroll
;                     for (int m = 0; m < 4; ++m) { const unsigned off = (unsigned)((PG8_ROW(u, ai, m) * DM + cb) * 4); xv[m][0] = ldb<f32x4>(xin, off); xv[m][1] = ldb<f32x4>(xin, off + 16); }
;                     PG8_FENCE();
; #pragma unroll
;                     for (int m = 0; m < 4; ++m) { const unsigned off = (unsigned)((PG8_ROW(u, ai, m) * DM + cb) * 2), offx = (unsigned)(PG8_ROW(u, ai, m) * (DM * 4) + DM * 2 + cb * 2);
;                         const f32x4 x0 = xv[m][0] + g0 * (acc[ai][bj][m][0] * rs[ai][m]), x1 = xv[m][1] + g1 * (acc[ai][bj][m][1] * rs[ai][m]);
;                         stb(xout, offx, pack8(x0, x1));
;                         if (gm) { ss[ai][m] += hsq4(x0) + hsq4(x1); stb(A, off, pack8(x0 * m0, x1 * m1)); } }
	v_cvt_pk_bf16_f32 v133, v120, v121
	v_pk_fma_f32 v[116:117], v[116:117], v[150:151], v[208:209]
	v_cvt_pk_bf16_f32 v134, v118, v119
	v_lshlrev_b32_e32 v199, 11, v136
	v_cvt_pk_bf16_f32 v135, v116, v117
	global_store_dwordx4 v137, v[132:135], s[8:9] nt
	v_add_u32_e32 v190, v199, v231
	v_pk_mul_f32 v[136:137], v[142:143], v[116:117]
	v_pk_mul_f32 v[132:133], v[144:145], v[122:123]
	v_pk_mul_f32 v[134:135], v[146:147], v[120:121]
	v_cvt_pk_bf16_f32 v132, v132, v133
	v_pk_mul_f32 v[138:139], v[140:141], v[118:119]
	v_cvt_pk_bf16_f32 v133, v134, v135
	v_add_u32_e32 v203, 0x80000, v171
	v_cvt_pk_bf16_f32 v134, v138, v139
	v_cvt_pk_bf16_f32 v135, v136, v137
	global_store_dwordx4 v190, v[132:135], s[20:21] nt
	v_add_u32_e32 v136, 48, v230
	v_lshlrev_b32_e32 v201, 12, v136
	v_pk_mul_f32 v[132:133], v[112:113], v[172:173] op_sel_hi:[1,0]
	v_pk_mul_f32 v[112:113], v[114:115], v[172:173] op_sel_hi:[1,0]
	v_pk_fma_f32 v[114:115], v[132:133], v[152:153], v[214:215]
	v_pk_mul_f32 v[132:133], v[108:109], v[172:173] op_sel_hi:[1,0]
	v_pk_mul_f32 v[108:109], v[110:111], v[172:173] op_sel_hi:[1,0]
	v_add_u32_e32 v137, v232, v201
	v_pk_fma_f32 v[112:113], v[112:113], v[154:155], v[216:217]
	v_pk_fma_f32 v[108:109], v[108:109], v[150:151], v[212:213]
	v_pk_fma_f32 v[110:111], v[132:133], v[148:149], v[210:211]
	v_cvt_pk_bf16_f32 v132, v114, v115
	v_cvt_pk_bf16_f32 v133, v112, v113
	v_lshlrev_b32_e32 v202, 11, v136
	v_cvt_pk_bf16_f32 v134, v110, v111
	v_cvt_pk_bf16_f32 v135, v108, v109
	global_store_dwordx4 v137, v[132:135], s[8:9] nt
	v_add_u32_e32 v190, v202, v231
	v_pk_mul_f32 v[136:137], v[142:143], v[108:109]
	v_pk_mul_f32 v[134:135], v[146:147], v[112:113]
	v_pk_mul_f32 v[132:133], v[144:145], v[114:115]
	v_pk_mul_f32 v[138:139], v[140:141], v[110:111]
	v_cvt_pk_bf16_f32 v132, v132, v133
	v_cvt_pk_bf16_f32 v133, v134, v135
	v_add_u32_e32 v204, 0x90000, v171
	v_cvt_pk_bf16_f32 v134, v138, v139
	v_cvt_pk_bf16_f32 v135, v136, v137
	global_store_dwordx4 v190, v[132:135], s[20:21] nt
	v_add_u32_e32 v136, v203, v189
	global_load_dwordx4 v[132:135], v136, s[2:3]
	s_nop 0
	global_load_dwordx4 v[136:139], v136, s[2:3] offset:16
	v_add_u32_e32 v190, v204, v189
	global_load_dwordx4 v[206:209], v190, s[2:3]
	global_load_dwordx4 v[210:213], v190, s[2:3] offset:16
	v_add_u32_e32 v205, 0xa0000, v171
	v_add_u32_e32 v190, v205, v189
	global_load_dwordx4 v[214:217], v190, s[2:3]
	global_load_dwordx4 v[218:221], v190, s[2:3] offset:16
	v_add_u32_e32 v190, 0xb0000, v171
	v_add_u32_e32 v189, v190, v189
	global_load_dwordx4 v[222:225], v189, s[2:3] offset:16
	global_load_dwordx4 v[226:229], v189, s[2:3]
	v_pk_mul_f32 v[192:193], v[104:105], v[170:171] op_sel_hi:[1,0]
	v_lshlrev_b32_e32 v189, 12, v191
	v_pk_mul_f32 v[104:105], v[106:107], v[170:171] op_sel_hi:[1,0]
	v_add_u32_e32 v194, v232, v189
	v_lshlrev_b32_e32 v191, 11, v191
	v_add_u32_e32 v196, 0xa0, v230
	v_mul_f32_e32 v179, v179, v179
	v_fmac_f32_e32 v179, v178, v178
	v_mul_f32_e32 v178, v181, v181
	v_mul_f32_e32 v177, v177, v177
	v_fmac_f32_e32 v178, v180, v180
	v_fmac_f32_e32 v177, v176, v176
	v_add_f32_e32 v176, v178, v177
	s_waitcnt vmcnt(7)
	v_pk_fma_f32 v[106:107], v[192:193], v[152:153], v[132:133]
	v_pk_mul_f32 v[132:133], v[100:101], v[170:171] op_sel_hi:[1,0]
	v_pk_fma_f32 v[104:105], v[104:105], v[154:155], v[134:135]
	v_pk_mul_f32 v[100:101], v[102:103], v[170:171] op_sel_hi:[1,0]
	s_waitcnt vmcnt(6)
	v_pk_fma_f32 v[102:103], v[132:133], v[148:149], v[136:137]
	v_cvt_pk_bf16_f32 v132, v106, v107
	v_cvt_pk_bf16_f32 v133, v104, v105
	v_pk_fma_f32 v[100:101], v[100:101], v[150:151], v[138:139]
	v_cvt_pk_bf16_f32 v134, v102, v103
	v_add_u32_e32 v192, v191, v231
	v_cvt_pk_bf16_f32 v135, v100, v101
	global_store_dwordx4 v194, v[132:135], s[8:9] nt
	v_pk_mul_f32 v[136:137], v[142:143], v[100:101]
	v_pk_mul_f32 v[138:139], v[140:141], v[102:103]
	v_pk_mul_f32 v[132:133], v[144:145], v[106:107]
	v_pk_mul_f32 v[134:135], v[146:147], v[104:105]
	v_cvt_pk_bf16_f32 v132, v132, v133
	s_nop 0
	v_cvt_pk_bf16_f32 v133, v134, v135
	v_cvt_pk_bf16_f32 v134, v138, v139
	v_cvt_pk_bf16_f32 v135, v136, v137
	global_store_dwordx4 v192, v[132:135], s[20:21] nt
	v_add_u32_e32 v136, 0x90, v230
	v_lshlrev_b32_e32 v192, 12, v136
	v_pk_mul_f32 v[132:133], v[96:97], v[168:169] op_sel_hi:[1,0]
	v_pk_mul_f32 v[96:97], v[98:99], v[168:169] op_sel_hi:[1,0]
	s_waitcnt vmcnt(7)
	v_pk_fma_f32 v[98:99], v[132:133], v[152:153], v[206:207]
	v_pk_mul_f32 v[132:133], v[92:93], v[168:169] op_sel_hi:[1,0]
	v_pk_mul_f32 v[92:93], v[94:95], v[168:169] op_sel_hi:[1,0]
	v_add_u32_e32 v137, v232, v192
	v_pk_fma_f32 v[96:97], v[96:97], v[154:155], v[208:209]
	s_waitcnt vmcnt(6)
	v_pk_fma_f32 v[92:93], v[92:93], v[150:151], v[212:213]
	v_pk_fma_f32 v[94:95], v[132:133], v[148:149], v[210:211]
	v_cvt_pk_bf16_f32 v132, v98, v99
	v_cvt_pk_bf16_f32 v133, v96, v97
	v_lshlrev_b32_e32 v193, 11, v136
	v_cvt_pk_bf16_f32 v134, v94, v95
	v_cvt_pk_bf16_f32 v135, v92, v93
	global_store_dwordx4 v137, v[132:135], s[8:9] nt
	v_add_u32_e32 v194, v193, v231
	v_pk_mul_f32 v[136:137], v[142:143], v[92:93]
	v_pk_mul_f32 v[134:135], v[146:147], v[96:97]
	v_pk_mul_f32 v[132:133], v[144:145], v[98:99]
	v_pk_mul_f32 v[138:139], v[140:141], v[94:95]
	v_cvt_pk_bf16_f32 v132, v132, v133
	v_cvt_pk_bf16_f32 v133, v134, v135
	v_add_u32_e32 v169, 0x80, v169
	v_cvt_pk_bf16_f32 v134, v138, v139
	v_cvt_pk_bf16_f32 v135, v136, v137
	global_store_dwordx4 v194, v[132:135], s[20:21] nt
	v_lshlrev_b32_e32 v194, 12, v196
	v_add_u32_e32 v198, v232, v194
	s_waitcnt vmcnt(7)
	v_pk_fma_f32 v[132:133], v[154:155], v[90:91], v[216:217]
	v_pk_fma_f32 v[136:137], v[152:153], v[88:89], v[214:215]
	s_waitcnt vmcnt(6)
; __device__ __forceinline__ u32x4 pack8(const f32x4& a, const f32x4& b) { u32x4 w; w.x = cvt_pk_bf16(a[0], a[1]); w.y = cvt_pk_bf16(a[2], a[3]); w.z = cvt_pk_bf16(b[0], b[1]); w.w = cvt_pk_bf16(b[2], b[3]); return w; }
; __device__ __forceinline__ float hsq4(const f32x4& a) { return (a[0] * a[0] + a[1] * a[1]) + (a[2] * a[2] + a[3] * a[3]); }
; #define PG8_FENCE() asm volatile("" ::: "memory")
;     __device__ __forceinline__ void operator()(const f32x4 (&acc)[2][2][4][2], const Unit& u, int wr, int wc, int fr, int fq) const {
;     ...
;         for (int bj = 0; bj < 2; ++bj) { const int cb = c0 + bj * HALF;
;             const f32x4 g0 = ldb<f32x4>(gate, (unsigned)((b * NMOD + cb) * 4)), g1 = ldb<f32x4>(gate, (unsigned)((b * NMOD + cb + 4) * 4));
;             f32x4 m0 = (f32x4){0.f, 0.f, 0.f, 0.f}, m1 = m0; if (gm) { m0 = ldb<f32x4>(gm, (unsigned)((b * DM + cb) * 4)); m1 = ldb<f32x4>(gm, (unsigned)((b * DM + cb + 4) * 4)); }
;             if (XF32) {
; #pragma unroll
;                 for (int ai = 0; ai < 2; ++ai) {
;                     f32x4 xv[4][2];
; #pragma unroll
;                     for (int m = 0; m < 4; ++m) { const unsigned off = (unsigned)((PG8_ROW(u, ai, m) * DM + cb) * 4); xv[m][0] = ldb<f32x4>(xin, off); xv[m][1] = ldb<f32x4>(xin, off + 16); }
;                     PG8_FENCE();
; #pragma unroll
;                     for (int m = 0; m < 4; ++m) { const unsigned off = (unsigned)((PG8_ROW(u, ai, m) * DM + cb) * 2), offx = (unsigned)(PG8_ROW(u, ai, m) * (DM * 4) + DM * 2 + cb * 2);
;                         const f32x4 x0 = xv[m][0] + g0 * (acc[ai][bj][m][0] * rs[ai][m]), x1 = xv[m][1] + g1 * (acc[ai][bj][m][1] * rs[ai][m]);
;                         stb(xout, offx, pack8(x0, x1));
;                         if (gm) { ss[ai][m] += hsq4(x0) + hsq4(x1); stb(A, off, pack8(x0 * m0, x1 * m1)); } }
	v_pk_fma_f32 v[138:139], v[84:85], v[148:149], v[218:219]
	v_cvt_pk_bf16_f32 v84, v136, v137
	v_cvt_pk_bf16_f32 v85, v132, v133
	v_pk_fma_f32 v[134:135], v[86:87], v[150:151], v[220:221]
	v_cvt_pk_bf16_f32 v86, v138, v139
	v_lshlrev_b32_e32 v196, 11, v196
	v_cvt_pk_bf16_f32 v87, v134, v135
	global_store_dwordx4 v198, v[84:87], s[8:9] nt
	v_add_u32_e32 v198, v196, v231
	v_pk_mul_f32 v[88:89], v[142:143], v[134:135]
	v_pk_mul_f32 v[84:85], v[144:145], v[136:137]
	v_pk_mul_f32 v[86:87], v[146:147], v[132:133]
	v_cvt_pk_bf16_f32 v84, v84, v85
	v_pk_mul_f32 v[90:91], v[140:141], v[138:139]
	v_cvt_pk_bf16_f32 v85, v86, v87
	s_waitcnt vmcnt(5)
	v_pk_fma_f32 v[154:155], v[154:155], v[82:83], v[228:229]
	v_cvt_pk_bf16_f32 v86, v90, v91
	v_cvt_pk_bf16_f32 v87, v88, v89
	global_store_dwordx4 v198, v[84:87], s[20:21] nt
	v_pk_fma_f32 v[152:153], v[152:153], v[80:81], v[226:227]
	v_pk_fma_f32 v[150:151], v[150:151], v[78:79], v[224:225]
	v_add_u32_e32 v84, 0xb0, v230
	v_lshlrev_b32_e32 v198, 12, v84
	v_add_u32_e32 v85, v232, v198
	v_pk_fma_f32 v[148:149], v[148:149], v[76:77], v[222:223]
	v_cvt_pk_bf16_f32 v76, v152, v153
	v_cvt_pk_bf16_f32 v77, v154, v155
	v_lshlrev_b32_e32 v200, 11, v84
	v_cvt_pk_bf16_f32 v78, v148, v149
	v_cvt_pk_bf16_f32 v79, v150, v151
	global_store_dwordx4 v85, v[76:79], s[8:9] nt
	v_add_u32_e32 v84, v200, v231
	v_pk_mul_f32 v[80:81], v[142:143], v[150:151]
	v_pk_mul_f32 v[78:79], v[146:147], v[154:155]
	v_pk_mul_f32 v[76:77], v[144:145], v[152:153]
	v_pk_mul_f32 v[82:83], v[140:141], v[148:149]
	v_cvt_pk_bf16_f32 v76, v76, v77
	v_cvt_pk_bf16_f32 v77, v78, v79
	v_lshlrev_b32_e32 v232, 2, v169
	v_cvt_pk_bf16_f32 v78, v82, v83
	v_cvt_pk_bf16_f32 v79, v80, v81
	global_store_dwordx4 v84, v[76:79], s[20:21] nt
	v_add_u32_e32 v80, s31, v232
	v_add_u32_e32 v11, v232, v11
	v_add_lshl_u32 v76, v169, s29, 2
	global_load_dwordx4 v[84:87], v76, s[16:17]
	v_add_u32_e32 v77, v232, v171
	v_or_b32_e32 v76, 16, v76
	global_load_dwordx4 v[140:143], v77, s[2:3]
	global_load_dwordx4 v[144:147], v77, s[2:3] offset:16
	global_load_dwordx4 v[88:91], v76, s[16:17]
	v_lshlrev_b32_e32 v169, 1, v169
	global_load_dwordx4 v[76:79], v80, s[18:19]
	v_or_b32_e32 v80, 16, v80
	global_load_dwordx4 v[80:83], v80, s[18:19]
	s_nop 0
	global_load_dwordx4 v[206:209], v11, s[2:3]
	global_load_dwordx4 v[210:213], v11, s[2:3] offset:16
	v_add_u32_e32 v11, v232, v173
	global_load_dwordx4 v[214:217], v11, s[2:3]
	global_load_dwordx4 v[218:221], v11, s[2:3] offset:16
	v_add_u32_e32 v11, v232, v188
	global_load_dwordx4 v[222:225], v11, s[2:3]
	global_load_dwordx4 v[226:229], v11, s[2:3] offset:16
	v_pk_mul_f32 v[230:231], v[72:73], v[186:187] op_sel_hi:[1,0]
	v_add_u32_e32 v11, 0x800, v169
	v_pk_mul_f32 v[72:73], v[74:75], v[186:187] op_sel_hi:[1,0]
	v_add_u32_e32 v171, v11, v175
	v_pk_mul_f32 v[12:13], v[12:13], v[10:11] op_sel_hi:[1,0]
	s_lshl_b32 s29, s34, 2
	s_or_b32 s29, s29, s56
	s_waitcnt vmcnt(10)
	v_pk_fma_f32 v[74:75], v[230:231], v[84:85], v[140:141]
	v_pk_mul_f32 v[140:141], v[68:69], v[186:187] op_sel_hi:[1,0]
	v_pk_fma_f32 v[72:73], v[72:73], v[86:87], v[142:143]
	v_pk_mul_f32 v[68:69], v[70:71], v[186:187] op_sel_hi:[1,0]
	s_waitcnt vmcnt(8)
	v_pk_fma_f32 v[70:71], v[140:141], v[88:89], v[144:145]
	v_cvt_pk_bf16_f32 v140, v74, v75
	v_cvt_pk_bf16_f32 v141, v72, v73
	v_pk_fma_f32 v[68:69], v[68:69], v[90:91], v[146:147]
	v_cvt_pk_bf16_f32 v142, v70, v71
	s_waitcnt vmcnt(6)
	v_pk_mul_f32 v[146:147], v[80:81], v[70:71]
	v_cvt_pk_bf16_f32 v143, v68, v69
	global_store_dwordx4 v171, v[140:143], s[8:9] nt
	v_add_u32_e32 v171, v169, v185
	v_pk_mul_f32 v[144:145], v[82:83], v[68:69]
	v_pk_mul_f32 v[140:141], v[76:77], v[74:75]
	v_pk_mul_f32 v[142:143], v[78:79], v[72:73]
	v_cvt_pk_bf16_f32 v140, v140, v141
	v_mul_f32_e32 v75, v75, v75
	v_cvt_pk_bf16_f32 v141, v142, v143
	v_cvt_pk_bf16_f32 v142, v146, v147
	v_cvt_pk_bf16_f32 v143, v144, v145
	global_store_dwordx4 v171, v[140:143], s[20:21] nt
	v_add_u32_e32 v144, v11, v187
	v_add_u32_e32 v171, v169, v195
	v_pk_mul_f32 v[140:141], v[64:65], v[184:185] op_sel_hi:[1,0]
	v_pk_mul_f32 v[64:65], v[66:67], v[184:185] op_sel_hi:[1,0]
	s_waitcnt vmcnt(7)
	v_pk_fma_f32 v[66:67], v[140:141], v[84:85], v[206:207]
	v_pk_mul_f32 v[140:141], v[60:61], v[184:185] op_sel_hi:[1,0]
	v_pk_fma_f32 v[64:65], v[64:65], v[86:87], v[208:209]
	v_pk_mul_f32 v[60:61], v[62:63], v[184:185] op_sel_hi:[1,0]
	s_waitcnt vmcnt(6)
	v_pk_fma_f32 v[62:63], v[140:141], v[88:89], v[210:211]
	v_cvt_pk_bf16_f32 v140, v66, v67
	v_cvt_pk_bf16_f32 v141, v64, v65
	v_pk_fma_f32 v[60:61], v[60:61], v[90:91], v[212:213]
	v_cvt_pk_bf16_f32 v142, v62, v63
	v_pk_mul_f32 v[146:147], v[80:81], v[62:63]
	v_cvt_pk_bf16_f32 v143, v60, v61
	global_store_dwordx4 v144, v[140:143], s[8:9] nt
	v_pk_mul_f32 v[144:145], v[82:83], v[60:61]
	v_mul_f32_e32 v73, v73, v73
	v_pk_mul_f32 v[140:141], v[76:77], v[66:67]
	v_pk_mul_f32 v[142:143], v[78:79], v[64:65]
	v_cvt_pk_bf16_f32 v140, v140, v141
	v_fmac_f32_e32 v75, v74, v74
	v_cvt_pk_bf16_f32 v141, v142, v143
	v_cvt_pk_bf16_f32 v142, v146, v147
	v_cvt_pk_bf16_f32 v143, v144, v145
	global_store_dwordx4 v171, v[140:143], s[20:21] nt
	v_add_u32_e32 v144, v11, v197
	v_add_u32_e32 v171, v169, v199
	v_pk_mul_f32 v[140:141], v[56:57], v[174:175] op_sel_hi:[1,0]
	v_pk_mul_f32 v[56:57], v[58:59], v[174:175] op_sel_hi:[1,0]
	s_waitcnt vmcnt(7)
	v_pk_fma_f32 v[58:59], v[140:141], v[84:85], v[214:215]
	v_pk_mul_f32 v[140:141], v[52:53], v[174:175] op_sel_hi:[1,0]
	v_pk_fma_f32 v[56:57], v[56:57], v[86:87], v[216:217]
	v_pk_mul_f32 v[52:53], v[54:55], v[174:175] op_sel_hi:[1,0]
	s_waitcnt vmcnt(6)
; __device__ __forceinline__ u32x4 pack8(const f32x4& a, const f32x4& b) { u32x4 w; w.x = cvt_pk_bf16(a[0], a[1]); w.y = cvt_pk_bf16(a[2], a[3]); w.z = cvt_pk_bf16(b[0], b[1]); w.w = cvt_pk_bf16(b[2], b[3]); return w; }
; __device__ __forceinline__ float hsq4(const f32x4& a) { return (a[0] * a[0] + a[1] * a[1]) + (a[2] * a[2] + a[3] * a[3]); }
; #define PG8_FENCE() asm volatile("" ::: "memory")
;     __device__ __forceinline__ void operator()(const f32x4 (&acc)[2][2][4][2], const Unit& u, int wr, int wc, int fr, int fq) const {
;     ...
;         for (int bj = 0; bj < 2; ++bj) { const int cb = c0 + bj * HALF;
;             const f32x4 g0 = ldb<f32x4>(gate, (unsigned)((b * NMOD + cb) * 4)), g1 = ldb<f32x4>(gate, (unsigned)((b * NMOD + cb + 4) * 4));
;             f32x4 m0 = (f32x4){0.f, 0.f, 0.f, 0.f}, m1 = m0; if (gm) { m0 = ldb<f32x4>(gm, (unsigned)((b * DM + cb) * 4)); m1 = ldb<f32x4>(gm, (unsigned)((b * DM + cb + 4) * 4)); }
;             if (XF32) {
; #pragma unroll
;                 for (int ai = 0; ai < 2; ++ai) {
;                     f32x4 xv[4][2];
; #pragma unroll
;                     for (int m = 0; m < 4; ++m) { const unsigned off = (unsigned)((PG8_ROW(u, ai, m) * DM + cb) * 4); xv[m][0] = ldb<f32x4>(xin, off); xv[m][1] = ldb<f32x4>(xin, off + 16); }
;                     PG8_FENCE();
; #pragma unroll
;                     for (int m = 0; m < 4; ++m) { const unsigned off = (unsigned)((PG8_ROW(u, ai, m) * DM + cb) * 2), offx = (unsigned)(PG8_ROW(u, ai, m) * (DM * 4) + DM * 2 + cb * 2);
;                         const f32x4 x0 = xv[m][0] + g0 * (acc[ai][bj][m][0] * rs[ai][m]), x1 = xv[m][1] + g1 * (acc[ai][bj][m][1] * rs[ai][m]);
;                         stb(xout, offx, pack8(x0, x1));
;                         if (gm) { ss[ai][m] += hsq4(x0) + hsq4(x1); stb(A, off, pack8(x0 * m0, x1 * m1)); } }
	v_pk_fma_f32 v[54:55], v[140:141], v[88:89], v[218:219]
	v_cvt_pk_bf16_f32 v140, v58, v59
	v_cvt_pk_bf16_f32 v141, v56, v57
	v_pk_fma_f32 v[52:53], v[52:53], v[90:91], v[220:221]
	v_cvt_pk_bf16_f32 v142, v54, v55
	v_pk_mul_f32 v[146:147], v[80:81], v[54:55]
	v_cvt_pk_bf16_f32 v143, v52, v53
	global_store_dwordx4 v144, v[140:143], s[8:9] nt
	v_pk_mul_f32 v[144:145], v[82:83], v[52:53]
	v_fmac_f32_e32 v73, v72, v72
	v_pk_mul_f32 v[140:141], v[76:77], v[58:59]
	v_pk_mul_f32 v[142:143], v[78:79], v[56:57]
	v_cvt_pk_bf16_f32 v140, v140, v141
	v_mul_f32_e32 v177, v71, v71
	v_cvt_pk_bf16_f32 v141, v142, v143
	v_cvt_pk_bf16_f32 v142, v146, v147
	v_cvt_pk_bf16_f32 v143, v144, v145
	global_store_dwordx4 v171, v[140:143], s[20:21] nt
	v_add_u32_e32 v144, v11, v201
	v_add_u32_e32 v171, v169, v202
	v_pk_mul_f32 v[140:141], v[48:49], v[172:173] op_sel_hi:[1,0]
	v_pk_mul_f32 v[48:49], v[50:51], v[172:173] op_sel_hi:[1,0]
	s_waitcnt vmcnt(7)
	v_pk_fma_f32 v[50:51], v[140:141], v[84:85], v[222:223]
	v_pk_mul_f32 v[140:141], v[44:45], v[172:173] op_sel_hi:[1,0]
	v_pk_mul_f32 v[44:45], v[46:47], v[172:173] op_sel_hi:[1,0]
	v_pk_fma_f32 v[48:49], v[48:49], v[86:87], v[224:225]
	s_waitcnt vmcnt(6)
	v_pk_fma_f32 v[44:45], v[44:45], v[90:91], v[228:229]
	v_pk_fma_f32 v[46:47], v[140:141], v[88:89], v[226:227]
	v_cvt_pk_bf16_f32 v140, v50, v51
	v_cvt_pk_bf16_f32 v141, v48, v49
	v_mul_f32_e32 v178, v69, v69
	v_cvt_pk_bf16_f32 v142, v46, v47
	v_cvt_pk_bf16_f32 v143, v44, v45
	global_store_dwordx4 v144, v[140:143], s[8:9] nt
	v_pk_mul_f32 v[144:145], v[82:83], v[44:45]
	v_pk_mul_f32 v[146:147], v[80:81], v[46:47]
	v_pk_mul_f32 v[142:143], v[78:79], v[48:49]
	v_pk_mul_f32 v[140:141], v[76:77], v[50:51]
	v_add_u32_e32 v72, v190, v232
	v_cvt_pk_bf16_f32 v140, v140, v141
	v_cvt_pk_bf16_f32 v141, v142, v143
	v_cvt_pk_bf16_f32 v142, v146, v147
	v_cvt_pk_bf16_f32 v143, v144, v145
	global_store_dwordx4 v171, v[140:143], s[20:21] nt
	v_add_u32_e32 v144, v232, v203
	global_load_dwordx4 v[140:143], v144, s[2:3]
	s_nop 0
	global_load_dwordx4 v[144:147], v144, s[2:3] offset:16
	v_add_u32_e32 v171, v204, v232
	global_load_dwordx4 v[172:175], v171, s[2:3]
	global_load_dwordx4 v[184:187], v171, s[2:3] offset:16
	v_add_u32_e32 v171, v205, v232
	global_load_dwordx4 v[202:205], v171, s[2:3]
	global_load_dwordx4 v[206:209], v171, s[2:3] offset:16
	v_mul_f32_e32 v171, v183, v183
	v_fmac_f32_e32 v171, v182, v182
	v_add_f32_e32 v171, v171, v179
	v_add_f32_e32 v171, v171, v176
	v_add_f32_e32 v176, v75, v73
	v_fmac_f32_e32 v177, v70, v70
	v_fmac_f32_e32 v178, v68, v68
	global_load_dwordx4 v[68:71], v72, s[2:3] offset:16
	s_nop 0
	global_load_dwordx4 v[72:75], v72, s[2:3]
	v_add_f32_e32 v177, v177, v178
	v_add_f32_e32 v176, v176, v177
	v_add_f32_e32 v171, v171, v176
	v_pk_mul_f32 v[176:177], v[40:41], v[170:171] op_sel_hi:[1,0]
	v_pk_mul_f32 v[40:41], v[42:43], v[170:171] op_sel_hi:[1,0]
	v_add_u32_e32 v178, v11, v189
	s_waitcnt vmcnt(7)
	v_pk_fma_f32 v[42:43], v[176:177], v[84:85], v[140:141]
	v_pk_mul_f32 v[140:141], v[36:37], v[170:171] op_sel_hi:[1,0]
	v_pk_fma_f32 v[40:41], v[40:41], v[86:87], v[142:143]
	v_pk_mul_f32 v[36:37], v[38:39], v[170:171] op_sel_hi:[1,0]
	s_waitcnt vmcnt(6)
	v_pk_fma_f32 v[38:39], v[140:141], v[88:89], v[144:145]
	v_cvt_pk_bf16_f32 v140, v42, v43
	v_cvt_pk_bf16_f32 v141, v40, v41
	v_pk_fma_f32 v[36:37], v[36:37], v[90:91], v[146:147]
	v_cvt_pk_bf16_f32 v142, v38, v39
	v_add_u32_e32 v170, v169, v191
	v_cvt_pk_bf16_f32 v143, v36, v37
	global_store_dwordx4 v178, v[140:143], s[8:9] nt
	v_pk_mul_f32 v[144:145], v[82:83], v[36:37]
	v_pk_mul_f32 v[146:147], v[80:81], v[38:39]
	v_pk_mul_f32 v[140:141], v[76:77], v[42:43]
	v_pk_mul_f32 v[142:143], v[78:79], v[40:41]
	v_cvt_pk_bf16_f32 v140, v140, v141
	s_waitcnt vmcnt(2)
; __device__ __forceinline__ u32x4 pack8(const f32x4& a, const f32x4& b) { u32x4 w; w.x = cvt_pk_bf16(a[0], a[1]); w.y = cvt_pk_bf16(a[2], a[3]); w.z = cvt_pk_bf16(b[0], b[1]); w.w = cvt_pk_bf16(b[2], b[3]); return w; }
; __device__ __forceinline__ float hsq4(const f32x4& a) { return (a[0] * a[0] + a[1] * a[1]) + (a[2] * a[2] + a[3] * a[3]); }
; #define PG8_FENCE() asm volatile("" ::: "memory")
;     __device__ __forceinline__ void operator()(const f32x4 (&acc)[2][2][4][2], const Unit& u, int wr, int wc, int fr, int fq) const {
;     ...
;                     for (int m = 0; m < 4; ++m) { const unsigned off = (unsigned)((PG8_ROW(u, ai, m) * DM + cb) * 2), offx = (unsigned)(PG8_ROW(u, ai, m) * (DM * 4) + DM * 2 + cb * 2);
;                         const f32x4 x0 = xv[m][0] + g0 * (acc[ai][bj][m][0] * rs[ai][m]), x1 = xv[m][1] + g1 * (acc[ai][bj][m][1] * rs[ai][m]);
;                         stb(xout, offx, pack8(x0, x1));
;                         if (gm) { ss[ai][m] += hsq4(x0) + hsq4(x1); stb(A, off, pack8(x0 * m0, x1 * m1)); } }
;                     PG8_FENCE(); }
;             } else {
;                 u32x4 xw[2][4];
; #pragma unroll
;                 for (int ai = 0; ai < 2; ++ai)
; #pragma unroll
;                     for (int m = 0; m < 4; ++m) xw[ai][m] = ldb<u32x4>(xin, (unsigned)(PG8_ROW(u, ai, m) * (DM * 4) + DM * 2 + cb * 2));
;                 PG8_FENCE();
; #pragma unroll
;                 for (int ai = 0; ai < 2; ++ai)
; #pragma unroll
;                     for (int m = 0; m < 4; ++m) { const unsigned off = (unsigned)((PG8_ROW(u, ai, m) * DM + cb) * 2), offx = (unsigned)(PG8_ROW(u, ai, m) * (DM * 4) + DM * 2 + cb * 2);
;                         const f32x4 x0 = bf_lo4(xw[ai][m]) + g0 * (acc[ai][bj][m][0] * rs[ai][m]), x1 = bf_hi4(xw[ai][m]) + g1 * (acc[ai][bj][m][1] * rs[ai][m]);
;                         stb(xout, offx, pack8(x0, x1));
;                         if (gm) { ss[ai][m] += hsq4(x0) + hsq4(x1); stb(A, off, pack8(x0 * m0, x1 * m1)); } }
;                 PG8_FENCE(); } }
;         if (gm) {
; #pragma unroll
;             for (int ai = 0; ai < 2; ++ai)
; #pragma unroll
;                 for (int m = 0; m < 4; ++m) { const float s = quad_sum(ss[ai][m]); if (fq == 0) stb(ssqo, (unsigned)((PG8_ROW(u, ai, m) * 16 + u.pn * 4 + wc) * 4), s); } }
	v_pk_fma_f32 v[12:13], v[12:13], v[88:89], v[68:69]
	v_cvt_pk_bf16_f32 v141, v142, v143
	v_cvt_pk_bf16_f32 v142, v146, v147
	v_cvt_pk_bf16_f32 v143, v144, v145
	global_store_dwordx4 v170, v[140:143], s[20:21] nt
	v_add_u32_e32 v144, v11, v192
	s_nop 0
	v_pk_mul_f32 v[140:141], v[32:33], v[168:169] op_sel_hi:[1,0]
	v_pk_mul_f32 v[32:33], v[34:35], v[168:169] op_sel_hi:[1,0]
	v_pk_fma_f32 v[34:35], v[140:141], v[84:85], v[172:173]
	v_pk_mul_f32 v[140:141], v[28:29], v[168:169] op_sel_hi:[1,0]
	v_pk_fma_f32 v[32:33], v[32:33], v[86:87], v[174:175]
	v_pk_mul_f32 v[28:29], v[30:31], v[168:169] op_sel_hi:[1,0]
	v_pk_fma_f32 v[30:31], v[140:141], v[88:89], v[184:185]
	v_cvt_pk_bf16_f32 v140, v34, v35
	v_cvt_pk_bf16_f32 v141, v32, v33
	v_pk_fma_f32 v[28:29], v[28:29], v[90:91], v[186:187]
	v_cvt_pk_bf16_f32 v142, v30, v31
	v_add_u32_e32 v168, v169, v193
	v_cvt_pk_bf16_f32 v143, v28, v29
	global_store_dwordx4 v144, v[140:143], s[8:9] nt
	v_pk_mul_f32 v[144:145], v[82:83], v[28:29]
	v_pk_mul_f32 v[146:147], v[80:81], v[30:31]
	v_pk_mul_f32 v[140:141], v[76:77], v[34:35]
	v_pk_mul_f32 v[142:143], v[78:79], v[32:33]
	v_cvt_pk_bf16_f32 v140, v140, v141
	s_nop 0
	v_cvt_pk_bf16_f32 v141, v142, v143
	v_cvt_pk_bf16_f32 v142, v146, v147
	v_cvt_pk_bf16_f32 v143, v144, v145
	global_store_dwordx4 v168, v[140:143], s[20:21] nt
	v_add_u32_e32 v144, v11, v194
	s_nop 0
	v_pk_mul_f32 v[140:141], v[24:25], v[166:167] op_sel_hi:[1,0]
	v_pk_mul_f32 v[24:25], v[26:27], v[166:167] op_sel_hi:[1,0]
	v_pk_fma_f32 v[26:27], v[140:141], v[84:85], v[202:203]
	v_pk_mul_f32 v[140:141], v[20:21], v[166:167] op_sel_hi:[1,0]
	v_pk_fma_f32 v[24:25], v[24:25], v[86:87], v[204:205]
	v_pk_mul_f32 v[20:21], v[22:23], v[166:167] op_sel_hi:[1,0]
	v_pk_fma_f32 v[22:23], v[140:141], v[88:89], v[206:207]
	v_cvt_pk_bf16_f32 v140, v26, v27
	v_cvt_pk_bf16_f32 v141, v24, v25
	v_pk_fma_f32 v[20:21], v[20:21], v[90:91], v[208:209]
	v_cvt_pk_bf16_f32 v142, v22, v23
	v_add_u32_e32 v166, v169, v196
	v_cvt_pk_bf16_f32 v143, v20, v21
	global_store_dwordx4 v144, v[140:143], s[8:9] nt
	v_pk_mul_f32 v[144:145], v[82:83], v[20:21]
	v_pk_mul_f32 v[146:147], v[80:81], v[22:23]
	v_pk_mul_f32 v[140:141], v[76:77], v[26:27]
	v_pk_mul_f32 v[142:143], v[78:79], v[24:25]
	v_cvt_pk_bf16_f32 v140, v140, v141
	s_nop 0
	v_cvt_pk_bf16_f32 v141, v142, v143
	v_cvt_pk_bf16_f32 v142, v146, v147
	v_cvt_pk_bf16_f32 v143, v144, v145
	global_store_dwordx4 v166, v[140:143], s[20:21] nt
	s_nop 1
	v_pk_mul_f32 v[140:141], v[16:17], v[10:11] op_sel_hi:[1,0]
	v_pk_mul_f32 v[16:17], v[18:19], v[10:11] op_sel_hi:[1,0]
	v_add_u32_e32 v142, v11, v198
	s_waitcnt vmcnt(6)
	v_pk_fma_f32 v[16:17], v[16:17], v[86:87], v[74:75]
	v_pk_fma_f32 v[18:19], v[140:141], v[84:85], v[72:73]
	v_pk_mul_f32 v[10:11], v[14:15], v[10:11] op_sel_hi:[1,0]
	v_cvt_pk_bf16_f32 v68, v18, v19
	v_cvt_pk_bf16_f32 v69, v16, v17
	v_pk_mul_f32 v[14:15], v[78:79], v[16:17]
	v_pk_fma_f32 v[10:11], v[10:11], v[90:91], v[70:71]
	v_cvt_pk_bf16_f32 v70, v12, v13
	v_add_u32_e32 v74, v169, v200
	v_cvt_pk_bf16_f32 v71, v10, v11
	global_store_dwordx4 v142, v[68:71], s[8:9] nt
	v_pk_mul_f32 v[72:73], v[82:83], v[10:11]
	s_nop 0
	v_pk_mul_f32 v[68:69], v[76:77], v[18:19]
	v_pk_mul_f32 v[70:71], v[80:81], v[12:13]
	v_cvt_pk_bf16_f32 v68, v68, v69
	v_cvt_pk_bf16_f32 v69, v14, v15
	ds_swizzle_b32 v14, v171 offset:swizzle(SWAP,16)
	v_cvt_pk_bf16_f32 v70, v70, v71
	v_cvt_pk_bf16_f32 v71, v72, v73
	global_store_dwordx4 v74, v[68:71], s[20:21] nt
	s_waitcnt lgkmcnt(0)
	v_add_f32_e32 v14, v171, v14
	v_mov_b32_e32 v15, v14
	s_nop 1
	v_permlane32_swap_b32_e32 v14, v15
	s_and_saveexec_b64 s[34:35], vcc
	s_cbranch_execz .LBB13_950
	s_lshl_b32 s31, s12, 14
	s_lshl_b32 s40, s29, 2
	s_add_i32 s40, s40, s31
	v_add_f32_e32 v14, v14, v15
	v_lshl_add_u32 v15, v9, 6, s40
	global_store_dword v15, v14, s[22:23]

; #define PG8_LAS __attribute__((address_space(3)))
; __device__ __forceinline__ float hsq4(const f32x4& a) { return (a[0] * a[0] + a[1] * a[1]) + (a[2] * a[2] + a[3] * a[3]); }
;     __device__ __forceinline__ void operator()(const f32x4 (&acc)[2][2][4][2], const Unit& u, int wr, int wc, int fr, int fq) const {
;     ...
;         if (MIDS) { PG8_LAS const unsigned char* sp = slds + RSTAT_OFF + (u.ui & 1) * 2048 + (wr * 64 + fr) * 8 + 4;
; #pragma unroll
;             for (int ai = 0; ai < 2; ++ai)
; #pragma unroll
;                 for (int m = 0; m < 4; ++m) rs[ai][m] = *(PG8_LAS const float*)(sp + (ai * 128 + m * 16) * 8);
;             PG8_FENCE(); }
; #pragma unroll
;         for (int bj = 0; bj < 2; ++bj) { const int cb = c0 + bj * HALF;
;             const f32x4 g0 = ldb<f32x4>(gate, (unsigned)((b * NMOD + cb) * 4)), g1 = ldb<f32x4>(gate, (unsigned)((b * NMOD + cb + 4) * 4));
;             f32x4 m0 = (f32x4){0.f, 0.f, 0.f, 0.f}, m1 = m0; if (gm) { m0 = ldb<f32x4>(gm, (unsigned)((b * DM + cb) * 4)); m1 = ldb<f32x4>(gm, (unsigned)((b * DM + cb + 4) * 4)); }
;             if (XF32) {
; #pragma unroll
;                 for (int ai = 0; ai < 2; ++ai) {
;                     f32x4 xv[4][2];
; #pragma unroll
;                     for (int m = 0; m < 4; ++m) { const unsigned off = (unsigned)((PG8_ROW(u, ai, m) * DM + cb) * 4); xv[m][0] = ldb<f32x4>(xin, off); xv[m][1] = ldb<f32x4>(xin, off + 16); }
;                     PG8_FENCE();
; #pragma unroll
;                     for (int m = 0; m < 4; ++m) { const unsigned off = (unsigned)((PG8_ROW(u, ai, m) * DM + cb) * 2), offx = (unsigned)(PG8_ROW(u, ai, m) * (DM * 4) + DM * 2 + cb * 2);
;                         const f32x4 x0 = xv[m][0] + g0 * (acc[ai][bj][m][0] * rs[ai][m]), x1 = xv[m][1] + g1 * (acc[ai][bj][m][1] * rs[ai][m]);
;                         stb(xout, offx, pack8(x0, x1));
;                         if (gm) { ss[ai][m] += hsq4(x0) + hsq4(x1); stb(A, off, pack8(x0 * m0, x1 * m1)); } }
;                     PG8_FENCE(); }
;             } else {
;                 u32x4 xw[2][4];
; #pragma unroll
;                 for (int ai = 0; ai < 2; ++ai)
; #pragma unroll
;                     for (int m = 0; m < 4; ++m) xw[ai][m] = ldb<u32x4>(xin, (unsigned)(PG8_ROW(u, ai, m) * (DM * 4) + DM * 2 + cb * 2));
;                 PG8_FENCE();
; #pragma unroll
;                 for (int ai = 0; ai < 2; ++ai)
; #pragma unroll
.LBB13_1926:
	v_mbcnt_lo_u32_b32 v9, -1, 0
	v_mbcnt_hi_u32_b32 v9, -1, v9
	s_lshl_b32 s27, s30, 8
	v_ashrrev_i32_e32 v11, 1, v9
	v_and_or_b32 v156, v9, 15, s55
	v_and_b32_e32 v11, -8, v11
	s_or_b32 s27, s27, s56
	v_lshlrev_b32_e32 v10, 3, v156
	v_add_u32_e32 v11, s27, v11
	v_add3_u32 v10, 0, v140, v10
	v_lshlrev_b32_e32 v216, 1, v11
	s_lshl_b32 s27, s12, 20
	v_add_u32_e32 v140, 0x21804, v10
	v_add_u32_e32 v141, 0x21884, v10
	v_add_u32_e32 v142, 0x21904, v10
	v_add_u32_e32 v143, 0x21984, v10
	v_add_u32_e32 v144, 0x21c04, v10
	v_add_u32_e32 v145, 0x21c84, v10
	v_add_u32_e32 v146, 0x21d04, v10
	v_add_u32_e32 v10, 0x21d84, v10
	v_add_u32_e32 v230, 0x800, v216
	v_lshl_add_u32 v185, v156, 12, s27
	s_ashr_i32 s29, s12, 3
	ds_read_b32 v202, v140
	ds_read_b32 v200, v141
	ds_read_b32 v198, v142
	ds_read_b32 v196, v143
	ds_read_b32 v186, v144
	ds_read_b32 v184, v145
	ds_read_b32 v182, v146
	ds_read_b32 v10, v10
	v_add_u32_e32 v140, v230, v185
	s_mul_i32 s27, s29, 0x1800
	global_load_dwordx4 v[188:191], v140, s[8:9]
	v_add_lshl_u32 v140, v11, s27, 2
	s_lshl_b32 s29, s29, 12
	global_load_dwordx4 v[152:155], v140, s[14:15]
	global_load_dwordx4 v[148:151], v140, s[14:15] offset:16
	v_lshl_add_u32 v140, v11, 2, s29
	global_load_dwordx4 v[144:147], v140, s[16:17]
	s_nop 0
	global_load_dwordx4 v[140:143], v140, s[16:17] offset:16
	v_or_b32_e32 v187, 0x10000, v185
	v_add_u32_e32 v157, v230, v187
	global_load_dwordx4 v[192:195], v157, s[8:9]
	v_or_b32_e32 v215, 0x20000, v185
	v_lshl_add_u32 v229, s12, 8, v156
	v_add_u32_e32 v156, v230, v215
	global_load_dwordx4 v[220:223], v156, s[8:9]
	v_or_b32_e32 v214, 0x30000, v185
	v_add_u32_e32 v213, 0x80000, v185
	v_add_u32_e32 v212, 0x90000, v185
	v_add_u32_e32 v203, 0xa0000, v185
	v_add_u32_e32 v201, 0xb0000, v185
	v_add_u32_e32 v157, v230, v214
	v_add_u32_e32 v156, v230, v213
	v_add_u32_e32 v158, v230, v212
	v_add_u32_e32 v159, v230, v203
	v_add_u32_e32 v204, v230, v201
	global_load_dwordx4 v[224:227], v157, s[8:9]
	global_load_dwordx4 v[168:171], v156, s[8:9]
	global_load_dwordx4 v[164:167], v158, s[8:9]
	global_load_dwordx4 v[160:163], v159, s[8:9]
	s_nop 0
	global_load_dwordx4 v[156:159], v204, s[8:9]
	v_lshlrev_b32_e32 v197, 12, v229
	s_waitcnt lgkmcnt(0)
	v_pk_mul_f32 v[136:137], v[136:137], v[202:203] op_sel_hi:[1,0]
	v_pk_mul_f32 v[138:139], v[138:139], v[202:203] op_sel_hi:[1,0]
	v_pk_mul_f32 v[132:133], v[132:133], v[202:203] op_sel_hi:[1,0]
	v_pk_mul_f32 v[134:135], v[134:135], v[202:203] op_sel_hi:[1,0]
	v_add_u32_e32 v218, v230, v197
	v_lshlrev_b32_e32 v199, 11, v229
	v_add_u32_e32 v217, v216, v199
	v_pk_mul_f32 v[108:109], v[108:109], v[196:197] op_sel_hi:[1,0]
	v_pk_mul_f32 v[110:111], v[110:111], v[196:197] op_sel_hi:[1,0]
	v_pk_mul_f32 v[104:105], v[104:105], v[186:187] op_sel_hi:[1,0]
	v_pk_mul_f32 v[106:107], v[106:107], v[186:187] op_sel_hi:[1,0]
	v_pk_mul_f32 v[100:101], v[100:101], v[186:187] op_sel_hi:[1,0]
	v_pk_mul_f32 v[102:103], v[102:103], v[186:187] op_sel_hi:[1,0]
	v_pk_mul_f32 v[96:97], v[96:97], v[184:185] op_sel_hi:[1,0]
	v_pk_mul_f32 v[98:99], v[98:99], v[184:185] op_sel_hi:[1,0]
	v_pk_mul_f32 v[92:93], v[92:93], v[184:185] op_sel_hi:[1,0]
	v_pk_mul_f32 v[94:95], v[94:95], v[184:185] op_sel_hi:[1,0]
	v_pk_mul_f32 v[88:89], v[88:89], v[182:183] op_sel_hi:[1,0]
	v_pk_mul_f32 v[90:91], v[90:91], v[182:183] op_sel_hi:[1,0]
	v_pk_mul_f32 v[84:85], v[84:85], v[182:183] op_sel_hi:[1,0]
	v_pk_mul_f32 v[86:87], v[86:87], v[182:183] op_sel_hi:[1,0]
	v_pk_mul_f32 v[80:81], v[80:81], v[10:11] op_sel_hi:[1,0]
	v_pk_mul_f32 v[82:83], v[82:83], v[10:11] op_sel_hi:[1,0]
	v_pk_mul_f32 v[76:77], v[76:77], v[10:11] op_sel_hi:[1,0]
	v_pk_mul_f32 v[78:79], v[78:79], v[10:11] op_sel_hi:[1,0]
	v_pk_mul_f32 v[74:75], v[74:75], v[202:203] op_sel_hi:[1,0]
	v_pk_mul_f32 v[72:73], v[72:73], v[202:203] op_sel_hi:[1,0]
	v_pk_mul_f32 v[68:69], v[68:69], v[202:203] op_sel_hi:[1,0]
	v_pk_mul_f32 v[70:71], v[70:71], v[202:203] op_sel_hi:[1,0]
	v_cmp_gt_u32_e32 vcc, 16, v9
	v_add_u32_e32 v9, s55, v9
	s_waitcnt vmcnt(0)
	v_lshlrev_b32_e32 v204, 16, v188
	v_and_b32_e32 v205, 0xffff0000, v188
	v_lshlrev_b32_e32 v188, 16, v189
	v_and_b32_e32 v189, 0xffff0000, v189
	v_lshlrev_b32_e32 v208, 16, v190
	v_and_b32_e32 v209, 0xffff0000, v190
	v_lshlrev_b32_e32 v190, 16, v191
	v_and_b32_e32 v191, 0xffff0000, v191
	v_pk_fma_f32 v[206:207], v[138:139], v[154:155], v[188:189]
	v_pk_fma_f32 v[210:211], v[136:137], v[152:153], v[204:205]
	v_pk_fma_f32 v[204:205], v[134:135], v[150:151], v[190:191]
	v_pk_fma_f32 v[208:209], v[132:133], v[148:149], v[208:209]
	v_cvt_pk_bf16_f32 v132, v210, v211
	v_cvt_pk_bf16_f32 v133, v206, v207
	v_pk_mul_f32 v[136:137], v[146:147], v[206:207]
	v_cvt_pk_bf16_f32 v134, v208, v209
	v_cvt_pk_bf16_f32 v135, v204, v205
	global_store_dwordx4 v218, v[132:135], s[8:9] nt
	v_pk_mul_f32 v[138:139], v[144:145], v[210:211]
	v_pk_mul_f32 v[188:189], v[142:143], v[204:205]
	v_pk_mul_f32 v[134:135], v[140:141], v[208:209]
	v_cvt_pk_bf16_f32 v132, v138, v139
	v_cvt_pk_bf16_f32 v133, v136, v137
	v_add_u32_e32 v138, 16, v229
	v_cvt_pk_bf16_f32 v134, v134, v135
	v_cvt_pk_bf16_f32 v135, v188, v189
	global_store_dwordx4 v217, v[132:135], s[18:19] nt
	v_pk_mul_f32 v[136:137], v[128:129], v[200:201] op_sel_hi:[1,0]
	v_pk_mul_f32 v[128:129], v[130:131], v[200:201] op_sel_hi:[1,0]
	v_lshlrev_b32_e32 v132, 16, v192
	v_and_b32_e32 v133, 0xffff0000, v192
	v_lshlrev_b32_e32 v134, 16, v193
	v_and_b32_e32 v135, 0xffff0000, v193
	v_lshlrev_b32_e32 v217, 12, v138
	v_pk_fma_f32 v[128:129], v[128:129], v[154:155], v[134:135]
	v_pk_fma_f32 v[130:131], v[136:137], v[152:153], v[132:133]
	v_lshlrev_b32_e32 v132, 16, v194
; __device__ __forceinline__ u32x4 pack8(const f32x4& a, const f32x4& b) { u32x4 w; w.x = cvt_pk_bf16(a[0], a[1]); w.y = cvt_pk_bf16(a[2], a[3]); w.z = cvt_pk_bf16(b[0], b[1]); w.w = cvt_pk_bf16(b[2], b[3]); return w; }
; __device__ __forceinline__ float hsq4(const f32x4& a) { return (a[0] * a[0] + a[1] * a[1]) + (a[2] * a[2] + a[3] * a[3]); }
; #define PG8_FENCE() asm volatile("" ::: "memory")
; __device__ __forceinline__ f32x4 bf_lo4(const u32x4& w) { f32x4 r; r[0] = __uint_as_float(w.x << 16); r[1] = __uint_as_float(w.x & 0xffff0000u); r[2] = __uint_as_float(w.y << 16); r[3] = __uint_as_float(w.y & 0xffff0000u); return r; }
; __device__ __forceinline__ f32x4 bf_hi4(const u32x4& w) { f32x4 r; r[0] = __uint_as_float(w.z << 16); r[1] = __uint_as_float(w.z & 0xffff0000u); r[2] = __uint_as_float(w.w << 16); r[3] = __uint_as_float(w.w & 0xffff0000u); return r; }
;     __device__ __forceinline__ void operator()(const f32x4 (&acc)[2][2][4][2], const Unit& u, int wr, int wc, int fr, int fq) const {
;     ...
;                 u32x4 xw[2][4];
; #pragma unroll
;                 for (int ai = 0; ai < 2; ++ai)
; #pragma unroll
;                     for (int m = 0; m < 4; ++m) xw[ai][m] = ldb<u32x4>(xin, (unsigned)(PG8_ROW(u, ai, m) * (DM * 4) + DM * 2 + cb * 2));
;                 PG8_FENCE();
; #pragma unroll
;                 for (int ai = 0; ai < 2; ++ai)
; #pragma unroll
;                     for (int m = 0; m < 4; ++m) { const unsigned off = (unsigned)((PG8_ROW(u, ai, m) * DM + cb) * 2), offx = (unsigned)(PG8_ROW(u, ai, m) * (DM * 4) + DM * 2 + cb * 2);
;                         const f32x4 x0 = bf_lo4(xw[ai][m]) + g0 * (acc[ai][bj][m][0] * rs[ai][m]), x1 = bf_hi4(xw[ai][m]) + g1 * (acc[ai][bj][m][1] * rs[ai][m]);
;                         stb(xout, offx, pack8(x0, x1));
;                         if (gm) { ss[ai][m] += hsq4(x0) + hsq4(x1); stb(A, off, pack8(x0 * m0, x1 * m1)); } }
;                 PG8_FENCE(); } }
	v_and_b32_e32 v133, 0xffff0000, v194
	v_lshlrev_b32_e32 v134, 16, v195
	v_and_b32_e32 v135, 0xffff0000, v195
	v_pk_mul_f32 v[136:137], v[124:125], v[200:201] op_sel_hi:[1,0]
	v_pk_mul_f32 v[124:125], v[126:127], v[200:201] op_sel_hi:[1,0]
	v_add_u32_e32 v139, v230, v217
	v_pk_fma_f32 v[124:125], v[124:125], v[150:151], v[134:135]
	v_pk_fma_f32 v[126:127], v[136:137], v[148:149], v[132:133]
	v_cvt_pk_bf16_f32 v132, v130, v131
	v_cvt_pk_bf16_f32 v133, v128, v129
	v_lshlrev_b32_e32 v218, 11, v138
	v_cvt_pk_bf16_f32 v134, v126, v127
	v_cvt_pk_bf16_f32 v135, v124, v125
	global_store_dwordx4 v139, v[132:135], s[8:9] nt
	v_add_u32_e32 v188, v218, v216
	v_pk_mul_f32 v[136:137], v[142:143], v[124:125]
	v_pk_mul_f32 v[134:135], v[146:147], v[128:129]
	v_pk_mul_f32 v[132:133], v[144:145], v[130:131]
	v_pk_mul_f32 v[138:139], v[140:141], v[126:127]
	v_cvt_pk_bf16_f32 v132, v132, v133
	v_cvt_pk_bf16_f32 v133, v134, v135
	s_nop 0
	v_cvt_pk_bf16_f32 v134, v138, v139
	v_cvt_pk_bf16_f32 v135, v136, v137
	global_store_dwordx4 v188, v[132:135], s[18:19] nt
	v_add_u32_e32 v138, 32, v229
	v_pk_mul_f32 v[136:137], v[120:121], v[198:199] op_sel_hi:[1,0]
	v_lshlrev_b32_e32 v132, 16, v220
	v_and_b32_e32 v133, 0xffff0000, v220
	v_lshlrev_b32_e32 v134, 16, v221
	v_and_b32_e32 v135, 0xffff0000, v221
	v_pk_mul_f32 v[120:121], v[122:123], v[198:199] op_sel_hi:[1,0]
	v_lshlrev_b32_e32 v219, 12, v138
	v_pk_fma_f32 v[120:121], v[120:121], v[154:155], v[134:135]
	v_pk_fma_f32 v[122:123], v[136:137], v[152:153], v[132:133]
	v_lshlrev_b32_e32 v132, 16, v222
	v_and_b32_e32 v133, 0xffff0000, v222
	v_lshlrev_b32_e32 v134, 16, v223
	v_and_b32_e32 v135, 0xffff0000, v223
	v_pk_mul_f32 v[136:137], v[116:117], v[198:199] op_sel_hi:[1,0]
	v_pk_mul_f32 v[116:117], v[118:119], v[198:199] op_sel_hi:[1,0]
	v_add_u32_e32 v139, v230, v219
	v_pk_fma_f32 v[116:117], v[116:117], v[150:151], v[134:135]
	v_pk_fma_f32 v[118:119], v[136:137], v[148:149], v[132:133]
	v_cvt_pk_bf16_f32 v132, v122, v123
	v_cvt_pk_bf16_f32 v133, v120, v121
	v_lshlrev_b32_e32 v220, 11, v138
	v_cvt_pk_bf16_f32 v134, v118, v119
	v_cvt_pk_bf16_f32 v135, v116, v117
	global_store_dwordx4 v139, v[132:135], s[8:9] nt
	v_add_u32_e32 v188, v220, v216
	v_pk_mul_f32 v[136:137], v[142:143], v[116:117]
	v_pk_mul_f32 v[134:135], v[146:147], v[120:121]
	v_pk_mul_f32 v[132:133], v[144:145], v[122:123]
	v_pk_mul_f32 v[138:139], v[140:141], v[118:119]
	v_cvt_pk_bf16_f32 v132, v132, v133
	v_cvt_pk_bf16_f32 v133, v134, v135
	s_nop 0
	v_cvt_pk_bf16_f32 v134, v138, v139
	v_cvt_pk_bf16_f32 v135, v136, v137
	global_store_dwordx4 v188, v[132:135], s[18:19] nt
	v_add_u32_e32 v138, 48, v229
	v_pk_mul_f32 v[136:137], v[112:113], v[196:197] op_sel_hi:[1,0]
	v_lshlrev_b32_e32 v134, 16, v225
	v_and_b32_e32 v135, 0xffff0000, v225
	v_pk_mul_f32 v[112:113], v[114:115], v[196:197] op_sel_hi:[1,0]
	v_lshlrev_b32_e32 v221, 12, v138
	v_lshlrev_b32_e32 v132, 16, v224
	v_and_b32_e32 v133, 0xffff0000, v224
	v_pk_fma_f32 v[112:113], v[112:113], v[154:155], v[134:135]
	v_lshlrev_b32_e32 v134, 16, v226
	v_and_b32_e32 v135, 0xffff0000, v226
	v_add_u32_e32 v139, v230, v221
	v_pk_fma_f32 v[114:115], v[136:137], v[152:153], v[132:133]
	v_lshlrev_b32_e32 v132, 16, v227
	v_and_b32_e32 v133, 0xffff0000, v227
	v_pk_fma_f32 v[134:135], v[108:109], v[148:149], v[134:135]
	v_cvt_pk_bf16_f32 v108, v114, v115
	v_cvt_pk_bf16_f32 v109, v112, v113
	v_pk_fma_f32 v[132:133], v[110:111], v[150:151], v[132:133]
	v_cvt_pk_bf16_f32 v110, v134, v135
	v_lshlrev_b32_e32 v222, 11, v138
	v_cvt_pk_bf16_f32 v111, v132, v133
	global_store_dwordx4 v139, v[108:111], s[8:9] nt
	v_add_u32_e32 v188, v222, v216
	v_pk_mul_f32 v[136:137], v[142:143], v[132:133]
	v_pk_mul_f32 v[108:109], v[144:145], v[114:115]
	v_pk_mul_f32 v[110:111], v[146:147], v[112:113]
	v_cvt_pk_bf16_f32 v108, v108, v109
	v_pk_mul_f32 v[138:139], v[140:141], v[134:135]
	v_cvt_pk_bf16_f32 v109, v110, v111
	s_nop 0
	v_cvt_pk_bf16_f32 v110, v138, v139
	v_cvt_pk_bf16_f32 v111, v136, v137
	global_store_dwordx4 v188, v[108:111], s[18:19] nt
	v_add_u32_e32 v188, 0x80, v229
	v_lshlrev_b32_e32 v223, 12, v188
	v_lshlrev_b32_e32 v108, 16, v168
	v_and_b32_e32 v109, 0xffff0000, v168
	v_lshlrev_b32_e32 v110, 16, v169
	v_and_b32_e32 v111, 0xffff0000, v169
	v_pk_fma_f32 v[138:139], v[104:105], v[152:153], v[108:109]
	v_lshlrev_b32_e32 v104, 16, v170
	v_and_b32_e32 v105, 0xffff0000, v170
	v_add_u32_e32 v189, v230, v223
	v_pk_fma_f32 v[136:137], v[106:107], v[154:155], v[110:111]
	v_lshlrev_b32_e32 v106, 16, v171
	v_and_b32_e32 v107, 0xffff0000, v171
	v_pk_fma_f32 v[170:171], v[100:101], v[148:149], v[104:105]
	v_cvt_pk_bf16_f32 v100, v138, v139
	v_cvt_pk_bf16_f32 v101, v136, v137
	v_pk_fma_f32 v[168:169], v[102:103], v[150:151], v[106:107]
	v_cvt_pk_bf16_f32 v102, v170, v171
	v_lshlrev_b32_e32 v224, 11, v188
	v_cvt_pk_bf16_f32 v103, v168, v169
	global_store_dwordx4 v189, v[100:103], s[8:9] nt
	v_add_u32_e32 v108, v224, v216
	v_pk_mul_f32 v[104:105], v[142:143], v[168:169]
	v_pk_mul_f32 v[100:101], v[144:145], v[138:139]
	v_pk_mul_f32 v[102:103], v[146:147], v[136:137]
	v_cvt_pk_bf16_f32 v100, v100, v101
	v_pk_mul_f32 v[106:107], v[140:141], v[170:171]
	v_cvt_pk_bf16_f32 v101, v102, v103
	s_nop 0
	v_cvt_pk_bf16_f32 v102, v106, v107
	v_cvt_pk_bf16_f32 v103, v104, v105
	global_store_dwordx4 v108, v[100:103], s[18:19] nt
	v_add_u32_e32 v104, 0x90, v229
	v_lshlrev_b32_e32 v225, 12, v104
	v_lshlrev_b32_e32 v100, 16, v164
	v_and_b32_e32 v101, 0xffff0000, v164
	v_lshlrev_b32_e32 v102, 16, v165
	v_and_b32_e32 v103, 0xffff0000, v165
	v_pk_fma_f32 v[188:189], v[96:97], v[152:153], v[100:101]
	v_lshlrev_b32_e32 v96, 16, v166
	v_and_b32_e32 v97, 0xffff0000, v166
; __device__ __forceinline__ u32x4 pack8(const f32x4& a, const f32x4& b) { u32x4 w; w.x = cvt_pk_bf16(a[0], a[1]); w.y = cvt_pk_bf16(a[2], a[3]); w.z = cvt_pk_bf16(b[0], b[1]); w.w = cvt_pk_bf16(b[2], b[3]); return w; }
; __device__ __forceinline__ float hsq4(const f32x4& a) { return (a[0] * a[0] + a[1] * a[1]) + (a[2] * a[2] + a[3] * a[3]); }
; #define PG8_FENCE() asm volatile("" ::: "memory")
; __device__ __forceinline__ f32x4 bf_lo4(const u32x4& w) { f32x4 r; r[0] = __uint_as_float(w.x << 16); r[1] = __uint_as_float(w.x & 0xffff0000u); r[2] = __uint_as_float(w.y << 16); r[3] = __uint_as_float(w.y & 0xffff0000u); return r; }
; __device__ __forceinline__ f32x4 bf_hi4(const u32x4& w) { f32x4 r; r[0] = __uint_as_float(w.z << 16); r[1] = __uint_as_float(w.z & 0xffff0000u); r[2] = __uint_as_float(w.w << 16); r[3] = __uint_as_float(w.w & 0xffff0000u); return r; }
;     __device__ __forceinline__ void operator()(const f32x4 (&acc)[2][2][4][2], const Unit& u, int wr, int wc, int fr, int fq) const {
;     ...
;                 u32x4 xw[2][4];
; #pragma unroll
;                 for (int ai = 0; ai < 2; ++ai)
; #pragma unroll
;                     for (int m = 0; m < 4; ++m) xw[ai][m] = ldb<u32x4>(xin, (unsigned)(PG8_ROW(u, ai, m) * (DM * 4) + DM * 2 + cb * 2));
;                 PG8_FENCE();
; #pragma unroll
;                 for (int ai = 0; ai < 2; ++ai)
; #pragma unroll
;                     for (int m = 0; m < 4; ++m) { const unsigned off = (unsigned)((PG8_ROW(u, ai, m) * DM + cb) * 2), offx = (unsigned)(PG8_ROW(u, ai, m) * (DM * 4) + DM * 2 + cb * 2);
;                         const f32x4 x0 = bf_lo4(xw[ai][m]) + g0 * (acc[ai][bj][m][0] * rs[ai][m]), x1 = bf_hi4(xw[ai][m]) + g1 * (acc[ai][bj][m][1] * rs[ai][m]);
;                         stb(xout, offx, pack8(x0, x1));
;                         if (gm) { ss[ai][m] += hsq4(x0) + hsq4(x1); stb(A, off, pack8(x0 * m0, x1 * m1)); } }
;                 PG8_FENCE(); } }
	v_add_u32_e32 v105, v230, v225
	v_pk_fma_f32 v[164:165], v[98:99], v[154:155], v[102:103]
	v_lshlrev_b32_e32 v98, 16, v167
	v_and_b32_e32 v99, 0xffff0000, v167
	v_pk_fma_f32 v[190:191], v[92:93], v[148:149], v[96:97]
	v_cvt_pk_bf16_f32 v92, v188, v189
	v_cvt_pk_bf16_f32 v93, v164, v165
	v_pk_fma_f32 v[166:167], v[94:95], v[150:151], v[98:99]
	v_cvt_pk_bf16_f32 v94, v190, v191
	v_lshlrev_b32_e32 v226, 11, v104
	v_cvt_pk_bf16_f32 v95, v166, v167
	global_store_dwordx4 v105, v[92:95], s[8:9] nt
	v_add_u32_e32 v100, v226, v216
	v_pk_mul_f32 v[96:97], v[142:143], v[166:167]
	v_pk_mul_f32 v[92:93], v[144:145], v[188:189]
	v_pk_mul_f32 v[94:95], v[146:147], v[164:165]
	v_cvt_pk_bf16_f32 v92, v92, v93
	v_pk_mul_f32 v[98:99], v[140:141], v[190:191]
	v_cvt_pk_bf16_f32 v93, v94, v95
	s_nop 0
	v_cvt_pk_bf16_f32 v94, v98, v99
	v_cvt_pk_bf16_f32 v95, v96, v97
	global_store_dwordx4 v100, v[92:95], s[18:19] nt
	v_add_u32_e32 v96, 0xa0, v229
	v_lshlrev_b32_e32 v227, 12, v96
	v_lshlrev_b32_e32 v92, 16, v160
	v_and_b32_e32 v93, 0xffff0000, v160
	v_lshlrev_b32_e32 v94, 16, v161
	v_and_b32_e32 v95, 0xffff0000, v161
	v_pk_fma_f32 v[192:193], v[152:153], v[88:89], v[92:93]
	v_lshlrev_b32_e32 v88, 16, v162
	v_and_b32_e32 v89, 0xffff0000, v162
	v_add_u32_e32 v97, v230, v227
	v_pk_fma_f32 v[160:161], v[154:155], v[90:91], v[94:95]
	v_lshlrev_b32_e32 v90, 16, v163
	v_and_b32_e32 v91, 0xffff0000, v163
	v_pk_fma_f32 v[194:195], v[84:85], v[148:149], v[88:89]
	v_cvt_pk_bf16_f32 v84, v192, v193
	v_cvt_pk_bf16_f32 v85, v160, v161
	v_pk_fma_f32 v[162:163], v[86:87], v[150:151], v[90:91]
	v_cvt_pk_bf16_f32 v86, v194, v195
	v_lshlrev_b32_e32 v228, 11, v96
	v_cvt_pk_bf16_f32 v87, v162, v163
	global_store_dwordx4 v97, v[84:87], s[8:9] nt
	v_add_u32_e32 v92, v228, v216
	v_pk_mul_f32 v[88:89], v[142:143], v[162:163]
	v_pk_mul_f32 v[84:85], v[144:145], v[192:193]
	v_pk_mul_f32 v[86:87], v[146:147], v[160:161]
	v_cvt_pk_bf16_f32 v84, v84, v85
	v_pk_mul_f32 v[90:91], v[140:141], v[194:195]
	v_cvt_pk_bf16_f32 v85, v86, v87
	v_mul_f32_e32 v93, v207, v207
	v_cvt_pk_bf16_f32 v86, v90, v91
	v_cvt_pk_bf16_f32 v87, v88, v89
	global_store_dwordx4 v92, v[84:87], s[18:19] nt
	v_add_u32_e32 v88, 0xb0, v229
	v_lshlrev_b32_e32 v229, 12, v88
	v_lshlrev_b32_e32 v84, 16, v156
	v_and_b32_e32 v85, 0xffff0000, v156
	v_lshlrev_b32_e32 v86, 16, v157
	v_and_b32_e32 v87, 0xffff0000, v157
	v_pk_fma_f32 v[152:153], v[152:153], v[80:81], v[84:85]
	v_lshlrev_b32_e32 v80, 16, v158
	v_and_b32_e32 v81, 0xffff0000, v158
	v_add_u32_e32 v89, v230, v229
	v_pk_fma_f32 v[154:155], v[154:155], v[82:83], v[86:87]
	v_lshlrev_b32_e32 v82, 16, v159
	v_and_b32_e32 v83, 0xffff0000, v159
	v_pk_fma_f32 v[148:149], v[148:149], v[76:77], v[80:81]
	v_cvt_pk_bf16_f32 v76, v152, v153
	v_cvt_pk_bf16_f32 v77, v154, v155
	v_pk_fma_f32 v[150:151], v[150:151], v[78:79], v[82:83]
	v_cvt_pk_bf16_f32 v78, v148, v149
	v_lshlrev_b32_e32 v156, 11, v88
	v_cvt_pk_bf16_f32 v79, v150, v151
	global_store_dwordx4 v89, v[76:79], s[8:9] nt
	v_add_u32_e32 v84, v156, v216
	v_pk_mul_f32 v[80:81], v[142:143], v[150:151]
	v_pk_mul_f32 v[76:77], v[144:145], v[152:153]
	v_pk_mul_f32 v[78:79], v[146:147], v[154:155]
	v_cvt_pk_bf16_f32 v76, v76, v77
	v_pk_mul_f32 v[82:83], v[140:141], v[148:149]
	v_cvt_pk_bf16_f32 v77, v78, v79
	v_fmac_f32_e32 v93, v206, v206
	v_cvt_pk_bf16_f32 v78, v82, v83
	v_cvt_pk_bf16_f32 v79, v80, v81
	global_store_dwordx4 v84, v[76:79], s[18:19] nt
	v_mul_f32_e32 v94, v205, v205
	v_fmac_f32_e32 v94, v204, v204
	v_add_u32_e32 v76, 0x80, v11
	v_lshlrev_b32_e32 v140, 1, v76
	v_add_u32_e32 v11, 0x800, v140
	v_add_u32_e32 v77, v11, v185
	v_add_u32_e32 v92, v11, v187
	global_load_dwordx4 v[142:145], v77, s[8:9]
	global_load_dwordx4 v[230:233], v92, s[8:9]
	v_add_lshl_u32 v77, v76, s27, 2
	global_load_dwordx4 v[88:91], v77, s[14:15]
	v_or_b32_e32 v77, 16, v77
	global_load_dwordx4 v[84:87], v77, s[14:15]
	v_lshl_add_u32 v80, v76, 2, s29
	global_load_dwordx4 v[76:79], v80, s[16:17]
	v_or_b32_e32 v80, 16, v80
	global_load_dwordx4 v[80:83], v80, s[16:17]
	v_mul_f32_e32 v92, v211, v211
	v_fmac_f32_e32 v92, v210, v210
	v_add_f32_e32 v92, v92, v93
	v_mul_f32_e32 v93, v209, v209
	v_fmac_f32_e32 v93, v208, v208
	v_add_f32_e32 v93, v93, v94
	v_add_f32_e32 v141, v92, v93
	v_add_u32_e32 v92, v11, v215
	v_add_u32_e32 v93, v11, v214
	global_load_dwordx4 v[204:207], v92, s[8:9]
	global_load_dwordx4 v[108:111], v93, s[8:9]
	v_add_u32_e32 v92, v11, v213
	v_add_u32_e32 v93, v11, v212
	global_load_dwordx4 v[104:107], v92, s[8:9]
	global_load_dwordx4 v[100:103], v93, s[8:9]
	v_add_u32_e32 v92, v11, v203
	v_add_u32_e32 v93, v11, v201
	global_load_dwordx4 v[96:99], v92, s[8:9]
	s_nop 0
	global_load_dwordx4 v[92:95], v93, s[8:9]
	v_add_u32_e32 v157, v11, v197
	v_pk_mul_f32 v[12:13], v[12:13], v[10:11] op_sel_hi:[1,0]
	s_lshl_b32 s27, s30, 2
	s_or_b32 s27, s27, s54
	s_waitcnt vmcnt(11)
	v_lshlrev_b32_e32 v146, 16, v142
	v_and_b32_e32 v147, 0xffff0000, v142
	v_lshlrev_b32_e32 v142, 16, v143
	v_and_b32_e32 v143, 0xffff0000, v143
	s_waitcnt vmcnt(9)
	v_pk_fma_f32 v[74:75], v[74:75], v[90:91], v[142:143]
	v_lshlrev_b32_e32 v142, 16, v144
	v_and_b32_e32 v143, 0xffff0000, v144
	v_lshlrev_b32_e32 v144, 16, v145
	v_and_b32_e32 v145, 0xffff0000, v145
	v_pk_fma_f32 v[72:73], v[72:73], v[88:89], v[146:147]
	s_waitcnt vmcnt(8)
	v_pk_fma_f32 v[144:145], v[70:71], v[86:87], v[144:145]
	v_pk_fma_f32 v[142:143], v[68:69], v[84:85], v[142:143]
	v_cvt_pk_bf16_f32 v68, v72, v73
	v_cvt_pk_bf16_f32 v69, v74, v75
	s_nop 0
	v_cvt_pk_bf16_f32 v70, v142, v143
	v_cvt_pk_bf16_f32 v71, v144, v145
	global_store_dwordx4 v157, v[68:71], s[8:9] nt
	s_nop 1
	v_mul_f32_e32 v68, v73, v73
	v_mul_f32_e32 v70, v75, v75
	v_fmac_f32_e32 v68, v72, v72
	v_fmac_f32_e32 v70, v74, v74
	v_add_f32_e32 v68, v68, v70
	v_mul_f32_e32 v70, v143, v143
	v_mul_f32_e32 v71, v145, v145
	v_fmac_f32_e32 v70, v142, v142
	v_fmac_f32_e32 v71, v144, v144
	v_add_f32_e32 v70, v70, v71
	v_add_f32_e32 v68, v68, v70
	s_waitcnt vmcnt(8)
; __device__ __forceinline__ u32x4 pack8(const f32x4& a, const f32x4& b) { u32x4 w; w.x = cvt_pk_bf16(a[0], a[1]); w.y = cvt_pk_bf16(a[2], a[3]); w.z = cvt_pk_bf16(b[0], b[1]); w.w = cvt_pk_bf16(b[2], b[3]); return w; }
; __device__ __forceinline__ float hsq4(const f32x4& a) { return (a[0] * a[0] + a[1] * a[1]) + (a[2] * a[2] + a[3] * a[3]); }
; #define PG8_FENCE() asm volatile("" ::: "memory")
; __device__ __forceinline__ f32x4 bf_lo4(const u32x4& w) { f32x4 r; r[0] = __uint_as_float(w.x << 16); r[1] = __uint_as_float(w.x & 0xffff0000u); r[2] = __uint_as_float(w.y << 16); r[3] = __uint_as_float(w.y & 0xffff0000u); return r; }
; __device__ __forceinline__ f32x4 bf_hi4(const u32x4& w) { f32x4 r; r[0] = __uint_as_float(w.z << 16); r[1] = __uint_as_float(w.z & 0xffff0000u); r[2] = __uint_as_float(w.w << 16); r[3] = __uint_as_float(w.w & 0xffff0000u); return r; }
;     __device__ __forceinline__ void operator()(const f32x4 (&acc)[2][2][4][2], const Unit& u, int wr, int wc, int fr, int fq) const {
;     ...
;                 u32x4 xw[2][4];
; #pragma unroll
;                 for (int ai = 0; ai < 2; ++ai)
; #pragma unroll
;                     for (int m = 0; m < 4; ++m) xw[ai][m] = ldb<u32x4>(xin, (unsigned)(PG8_ROW(u, ai, m) * (DM * 4) + DM * 2 + cb * 2));
;                 PG8_FENCE();
; #pragma unroll
;                 for (int ai = 0; ai < 2; ++ai)
; #pragma unroll
;                     for (int m = 0; m < 4; ++m) { const unsigned off = (unsigned)((PG8_ROW(u, ai, m) * DM + cb) * 2), offx = (unsigned)(PG8_ROW(u, ai, m) * (DM * 4) + DM * 2 + cb * 2);
;                         const f32x4 x0 = bf_lo4(xw[ai][m]) + g0 * (acc[ai][bj][m][0] * rs[ai][m]), x1 = bf_hi4(xw[ai][m]) + g1 * (acc[ai][bj][m][1] * rs[ai][m]);
;                         stb(xout, offx, pack8(x0, x1));
;                         if (gm) { ss[ai][m] += hsq4(x0) + hsq4(x1); stb(A, off, pack8(x0 * m0, x1 * m1)); } }
;                 PG8_FENCE(); } }
	v_pk_mul_f32 v[70:71], v[76:77], v[72:73]
	v_add_u32_e32 v69, v140, v199
	v_pk_mul_f32 v[74:75], v[78:79], v[74:75]
	s_waitcnt vmcnt(7)
	v_pk_mul_f32 v[72:73], v[80:81], v[142:143]
	v_cvt_pk_bf16_f32 v70, v70, v71
	v_cvt_pk_bf16_f32 v71, v74, v75
	v_pk_mul_f32 v[144:145], v[82:83], v[144:145]
	v_cvt_pk_bf16_f32 v72, v72, v73
	v_pk_mul_f32 v[74:75], v[64:65], v[200:201] op_sel_hi:[1,0]
	v_cvt_pk_bf16_f32 v73, v144, v145
	global_store_dwordx4 v69, v[70:73], s[18:19] nt
	v_pk_mul_f32 v[64:65], v[66:67], v[200:201] op_sel_hi:[1,0]
	v_add_u32_e32 v69, v11, v217
	v_lshlrev_b32_e32 v70, 16, v230
	v_and_b32_e32 v71, 0xffff0000, v230
	v_lshlrev_b32_e32 v72, 16, v231
	v_and_b32_e32 v73, 0xffff0000, v231
	v_pk_fma_f32 v[66:67], v[74:75], v[88:89], v[70:71]
	v_lshlrev_b32_e32 v70, 16, v232
	v_and_b32_e32 v71, 0xffff0000, v232
	v_pk_mul_f32 v[74:75], v[60:61], v[200:201] op_sel_hi:[1,0]
	v_pk_fma_f32 v[64:65], v[64:65], v[90:91], v[72:73]
	v_lshlrev_b32_e32 v72, 16, v233
	v_and_b32_e32 v73, 0xffff0000, v233
	v_pk_mul_f32 v[60:61], v[62:63], v[200:201] op_sel_hi:[1,0]
	v_pk_fma_f32 v[62:63], v[74:75], v[84:85], v[70:71]
	v_cvt_pk_bf16_f32 v70, v66, v67
	v_cvt_pk_bf16_f32 v71, v64, v65
	v_pk_fma_f32 v[60:61], v[60:61], v[86:87], v[72:73]
	v_cvt_pk_bf16_f32 v72, v62, v63
	v_pk_mul_f32 v[142:143], v[80:81], v[62:63]
	v_cvt_pk_bf16_f32 v73, v60, v61
	global_store_dwordx4 v69, v[70:73], s[8:9] nt
	v_add_u32_e32 v69, v140, v218
	v_pk_mul_f32 v[74:75], v[82:83], v[60:61]
	v_pk_mul_f32 v[70:71], v[76:77], v[66:67]
	v_pk_mul_f32 v[72:73], v[78:79], v[64:65]
	v_cvt_pk_bf16_f32 v70, v70, v71
	v_add_f32_e32 v68, v141, v68
	v_cvt_pk_bf16_f32 v71, v72, v73
	v_cvt_pk_bf16_f32 v72, v142, v143
	v_cvt_pk_bf16_f32 v73, v74, v75
	global_store_dwordx4 v69, v[70:73], s[18:19] nt
	v_pk_mul_f32 v[74:75], v[56:57], v[198:199] op_sel_hi:[1,0]
	v_pk_mul_f32 v[56:57], v[58:59], v[198:199] op_sel_hi:[1,0]
	s_waitcnt vmcnt(9)
	v_lshlrev_b32_e32 v70, 16, v204
	v_and_b32_e32 v71, 0xffff0000, v204
	v_lshlrev_b32_e32 v72, 16, v205
	v_and_b32_e32 v73, 0xffff0000, v205
	v_pk_fma_f32 v[58:59], v[74:75], v[88:89], v[70:71]
	v_lshlrev_b32_e32 v70, 16, v206
	v_and_b32_e32 v71, 0xffff0000, v206
	v_pk_mul_f32 v[74:75], v[52:53], v[198:199] op_sel_hi:[1,0]
	v_add_u32_e32 v69, v11, v219
	v_pk_fma_f32 v[56:57], v[56:57], v[90:91], v[72:73]
	v_lshlrev_b32_e32 v72, 16, v207
	v_and_b32_e32 v73, 0xffff0000, v207
	v_pk_mul_f32 v[52:53], v[54:55], v[198:199] op_sel_hi:[1,0]
	v_pk_fma_f32 v[54:55], v[74:75], v[84:85], v[70:71]
	v_cvt_pk_bf16_f32 v70, v58, v59
	v_cvt_pk_bf16_f32 v71, v56, v57
	v_pk_fma_f32 v[52:53], v[52:53], v[86:87], v[72:73]
	v_cvt_pk_bf16_f32 v72, v54, v55
	v_pk_mul_f32 v[142:143], v[80:81], v[54:55]
	v_cvt_pk_bf16_f32 v73, v52, v53
	global_store_dwordx4 v69, v[70:73], s[8:9] nt
	v_add_u32_e32 v69, v140, v220
	v_pk_mul_f32 v[74:75], v[82:83], v[52:53]
	v_pk_mul_f32 v[70:71], v[76:77], v[58:59]
	v_pk_mul_f32 v[72:73], v[78:79], v[56:57]
	v_cvt_pk_bf16_f32 v70, v70, v71
	s_nop 0
	v_cvt_pk_bf16_f32 v71, v72, v73
	v_cvt_pk_bf16_f32 v72, v142, v143
	v_cvt_pk_bf16_f32 v73, v74, v75
	global_store_dwordx4 v69, v[70:73], s[18:19] nt
	v_pk_mul_f32 v[74:75], v[48:49], v[196:197] op_sel_hi:[1,0]
	v_pk_mul_f32 v[48:49], v[50:51], v[196:197] op_sel_hi:[1,0]
	s_waitcnt vmcnt(10)
	v_lshlrev_b32_e32 v70, 16, v108
	v_and_b32_e32 v71, 0xffff0000, v108
	v_lshlrev_b32_e32 v72, 16, v109
	v_and_b32_e32 v73, 0xffff0000, v109
	v_pk_fma_f32 v[50:51], v[74:75], v[88:89], v[70:71]
	v_lshlrev_b32_e32 v70, 16, v110
	v_and_b32_e32 v71, 0xffff0000, v110
	v_pk_mul_f32 v[74:75], v[44:45], v[196:197] op_sel_hi:[1,0]
	v_add_u32_e32 v69, v11, v221
	v_pk_fma_f32 v[48:49], v[48:49], v[90:91], v[72:73]
	v_lshlrev_b32_e32 v72, 16, v111
	v_and_b32_e32 v73, 0xffff0000, v111
	v_pk_mul_f32 v[44:45], v[46:47], v[196:197] op_sel_hi:[1,0]
	v_pk_fma_f32 v[46:47], v[74:75], v[84:85], v[70:71]
	v_cvt_pk_bf16_f32 v70, v50, v51
	v_cvt_pk_bf16_f32 v71, v48, v49
	v_pk_fma_f32 v[44:45], v[44:45], v[86:87], v[72:73]
	v_cvt_pk_bf16_f32 v72, v46, v47
	v_pk_mul_f32 v[108:109], v[80:81], v[46:47]
	v_cvt_pk_bf16_f32 v73, v44, v45
	global_store_dwordx4 v69, v[70:73], s[8:9] nt
	v_add_u32_e32 v69, v140, v222
	v_pk_mul_f32 v[74:75], v[82:83], v[44:45]
	v_pk_mul_f32 v[70:71], v[76:77], v[50:51]
	v_pk_mul_f32 v[72:73], v[78:79], v[48:49]
	v_cvt_pk_bf16_f32 v70, v70, v71
	s_nop 0
	v_cvt_pk_bf16_f32 v71, v72, v73
	v_cvt_pk_bf16_f32 v72, v108, v109
	v_cvt_pk_bf16_f32 v73, v74, v75
	global_store_dwordx4 v69, v[70:73], s[18:19] nt
	v_pk_mul_f32 v[74:75], v[40:41], v[186:187] op_sel_hi:[1,0]
	v_pk_mul_f32 v[40:41], v[42:43], v[186:187] op_sel_hi:[1,0]
	s_waitcnt vmcnt(11)
; __device__ __forceinline__ u32x4 pack8(const f32x4& a, const f32x4& b) { u32x4 w; w.x = cvt_pk_bf16(a[0], a[1]); w.y = cvt_pk_bf16(a[2], a[3]); w.z = cvt_pk_bf16(b[0], b[1]); w.w = cvt_pk_bf16(b[2], b[3]); return w; }
; __device__ __forceinline__ float hsq4(const f32x4& a) { return (a[0] * a[0] + a[1] * a[1]) + (a[2] * a[2] + a[3] * a[3]); }
; __device__ __forceinline__ float quad_sum(float s) { s += swz_xor16(s); auto rr = __builtin_amdgcn_permlane32_swap(__float_as_uint(s), __float_as_uint(s), false, false); return __uint_as_float(rr[0]) + __uint_as_float(rr[1]); }
; #define PG8_FENCE() asm volatile("" ::: "memory")
; __device__ __forceinline__ f32x4 bf_lo4(const u32x4& w) { f32x4 r; r[0] = __uint_as_float(w.x << 16); r[1] = __uint_as_float(w.x & 0xffff0000u); r[2] = __uint_as_float(w.y << 16); r[3] = __uint_as_float(w.y & 0xffff0000u); return r; }
; __device__ __forceinline__ f32x4 bf_hi4(const u32x4& w) { f32x4 r; r[0] = __uint_as_float(w.z << 16); r[1] = __uint_as_float(w.z & 0xffff0000u); r[2] = __uint_as_float(w.w << 16); r[3] = __uint_as_float(w.w & 0xffff0000u); return r; }
;     __device__ __forceinline__ void operator()(const f32x4 (&acc)[2][2][4][2], const Unit& u, int wr, int wc, int fr, int fq) const {
;     ...
; #pragma unroll
;                 for (int ai = 0; ai < 2; ++ai)
; #pragma unroll
;                     for (int m = 0; m < 4; ++m) { const unsigned off = (unsigned)((PG8_ROW(u, ai, m) * DM + cb) * 2), offx = (unsigned)(PG8_ROW(u, ai, m) * (DM * 4) + DM * 2 + cb * 2);
;                         const f32x4 x0 = bf_lo4(xw[ai][m]) + g0 * (acc[ai][bj][m][0] * rs[ai][m]), x1 = bf_hi4(xw[ai][m]) + g1 * (acc[ai][bj][m][1] * rs[ai][m]);
;                         stb(xout, offx, pack8(x0, x1));
;                         if (gm) { ss[ai][m] += hsq4(x0) + hsq4(x1); stb(A, off, pack8(x0 * m0, x1 * m1)); } }
;                 PG8_FENCE(); } }
;         if (gm) {
; #pragma unroll
;             for (int ai = 0; ai < 2; ++ai)
; #pragma unroll
;                 for (int m = 0; m < 4; ++m) { const float s = quad_sum(ss[ai][m]); if (fq == 0) stb(ssqo, (unsigned)((PG8_ROW(u, ai, m) * 16 + u.pn * 4 + wc) * 4), s); } }
	v_lshlrev_b32_e32 v70, 16, v104
	v_and_b32_e32 v71, 0xffff0000, v104
	v_lshlrev_b32_e32 v72, 16, v105
	v_and_b32_e32 v73, 0xffff0000, v105
	v_pk_fma_f32 v[42:43], v[74:75], v[88:89], v[70:71]
	v_lshlrev_b32_e32 v70, 16, v106
	v_and_b32_e32 v71, 0xffff0000, v106
	v_pk_mul_f32 v[74:75], v[36:37], v[186:187] op_sel_hi:[1,0]
	v_add_u32_e32 v69, v11, v223
	v_pk_fma_f32 v[40:41], v[40:41], v[90:91], v[72:73]
	v_lshlrev_b32_e32 v72, 16, v107
	v_and_b32_e32 v73, 0xffff0000, v107
	v_pk_mul_f32 v[36:37], v[38:39], v[186:187] op_sel_hi:[1,0]
	v_pk_fma_f32 v[38:39], v[74:75], v[84:85], v[70:71]
	v_cvt_pk_bf16_f32 v70, v42, v43
	v_cvt_pk_bf16_f32 v71, v40, v41
	v_pk_fma_f32 v[36:37], v[36:37], v[86:87], v[72:73]
	v_cvt_pk_bf16_f32 v72, v38, v39
	v_pk_mul_f32 v[104:105], v[80:81], v[38:39]
	v_cvt_pk_bf16_f32 v73, v36, v37
	global_store_dwordx4 v69, v[70:73], s[8:9] nt
	v_add_u32_e32 v69, v140, v224
	v_pk_mul_f32 v[74:75], v[82:83], v[36:37]
	v_pk_mul_f32 v[70:71], v[76:77], v[42:43]
	v_pk_mul_f32 v[72:73], v[78:79], v[40:41]
	v_cvt_pk_bf16_f32 v70, v70, v71
	s_nop 0
	v_cvt_pk_bf16_f32 v71, v72, v73
	v_cvt_pk_bf16_f32 v72, v104, v105
	v_cvt_pk_bf16_f32 v73, v74, v75
	global_store_dwordx4 v69, v[70:73], s[18:19] nt
	v_pk_mul_f32 v[74:75], v[32:33], v[184:185] op_sel_hi:[1,0]
	v_pk_mul_f32 v[32:33], v[34:35], v[184:185] op_sel_hi:[1,0]
	s_waitcnt vmcnt(12)
	v_lshlrev_b32_e32 v70, 16, v100
	v_and_b32_e32 v71, 0xffff0000, v100
	v_lshlrev_b32_e32 v72, 16, v101
	v_and_b32_e32 v73, 0xffff0000, v101
	v_pk_fma_f32 v[34:35], v[74:75], v[88:89], v[70:71]
	v_lshlrev_b32_e32 v70, 16, v102
	v_and_b32_e32 v71, 0xffff0000, v102
	v_pk_mul_f32 v[74:75], v[28:29], v[184:185] op_sel_hi:[1,0]
	v_add_u32_e32 v69, v11, v225
	v_pk_fma_f32 v[32:33], v[32:33], v[90:91], v[72:73]
	v_lshlrev_b32_e32 v72, 16, v103
	v_and_b32_e32 v73, 0xffff0000, v103
	v_pk_mul_f32 v[28:29], v[30:31], v[184:185] op_sel_hi:[1,0]
	v_pk_fma_f32 v[30:31], v[74:75], v[84:85], v[70:71]
	v_cvt_pk_bf16_f32 v70, v34, v35
	v_cvt_pk_bf16_f32 v71, v32, v33
	v_pk_fma_f32 v[28:29], v[28:29], v[86:87], v[72:73]
	v_cvt_pk_bf16_f32 v72, v30, v31
	v_pk_mul_f32 v[100:101], v[80:81], v[30:31]
	v_cvt_pk_bf16_f32 v73, v28, v29
	global_store_dwordx4 v69, v[70:73], s[8:9] nt
	v_add_u32_e32 v69, v140, v226
	v_pk_mul_f32 v[74:75], v[82:83], v[28:29]
	v_pk_mul_f32 v[70:71], v[76:77], v[34:35]
	v_pk_mul_f32 v[72:73], v[78:79], v[32:33]
	v_cvt_pk_bf16_f32 v70, v70, v71
	s_nop 0
	v_cvt_pk_bf16_f32 v71, v72, v73
	v_cvt_pk_bf16_f32 v72, v100, v101
	v_cvt_pk_bf16_f32 v73, v74, v75
	global_store_dwordx4 v69, v[70:73], s[18:19] nt
	v_pk_mul_f32 v[74:75], v[24:25], v[182:183] op_sel_hi:[1,0]
	v_pk_mul_f32 v[24:25], v[26:27], v[182:183] op_sel_hi:[1,0]
	s_waitcnt vmcnt(13)
	v_lshlrev_b32_e32 v70, 16, v96
	v_and_b32_e32 v71, 0xffff0000, v96
	v_lshlrev_b32_e32 v72, 16, v97
	v_and_b32_e32 v73, 0xffff0000, v97
	v_pk_fma_f32 v[26:27], v[74:75], v[88:89], v[70:71]
	v_lshlrev_b32_e32 v70, 16, v98
	v_and_b32_e32 v71, 0xffff0000, v98
	v_pk_mul_f32 v[74:75], v[20:21], v[182:183] op_sel_hi:[1,0]
	v_add_u32_e32 v69, v11, v227
	v_pk_fma_f32 v[24:25], v[24:25], v[90:91], v[72:73]
	v_lshlrev_b32_e32 v72, 16, v99
	v_and_b32_e32 v73, 0xffff0000, v99
	v_pk_mul_f32 v[20:21], v[22:23], v[182:183] op_sel_hi:[1,0]
	v_pk_fma_f32 v[22:23], v[74:75], v[84:85], v[70:71]
	v_cvt_pk_bf16_f32 v70, v26, v27
	v_cvt_pk_bf16_f32 v71, v24, v25
	v_pk_fma_f32 v[20:21], v[20:21], v[86:87], v[72:73]
	v_cvt_pk_bf16_f32 v72, v22, v23
	v_pk_mul_f32 v[96:97], v[80:81], v[22:23]
	v_cvt_pk_bf16_f32 v73, v20, v21
	global_store_dwordx4 v69, v[70:73], s[8:9] nt
	v_add_u32_e32 v69, v140, v228
	v_pk_mul_f32 v[74:75], v[82:83], v[20:21]
	v_pk_mul_f32 v[70:71], v[76:77], v[26:27]
	v_pk_mul_f32 v[72:73], v[78:79], v[24:25]
	v_cvt_pk_bf16_f32 v70, v70, v71
	s_nop 0
	v_cvt_pk_bf16_f32 v71, v72, v73
	v_cvt_pk_bf16_f32 v72, v96, v97
	v_cvt_pk_bf16_f32 v73, v74, v75
	global_store_dwordx4 v69, v[70:73], s[18:19] nt
	v_pk_mul_f32 v[74:75], v[16:17], v[10:11] op_sel_hi:[1,0]
	v_pk_mul_f32 v[16:17], v[18:19], v[10:11] op_sel_hi:[1,0]
	s_waitcnt vmcnt(14)
	v_lshlrev_b32_e32 v70, 16, v92
	v_and_b32_e32 v71, 0xffff0000, v92
	v_lshlrev_b32_e32 v72, 16, v93
	v_and_b32_e32 v73, 0xffff0000, v93
	v_pk_fma_f32 v[18:19], v[74:75], v[88:89], v[70:71]
	v_lshlrev_b32_e32 v70, 16, v94
	v_and_b32_e32 v71, 0xffff0000, v94
	v_add_u32_e32 v69, v11, v229
	v_pk_fma_f32 v[16:17], v[16:17], v[90:91], v[72:73]
	v_lshlrev_b32_e32 v72, 16, v95
	v_and_b32_e32 v73, 0xffff0000, v95
	v_pk_mul_f32 v[10:11], v[14:15], v[10:11] op_sel_hi:[1,0]
	v_pk_fma_f32 v[12:13], v[12:13], v[84:85], v[70:71]
	v_cvt_pk_bf16_f32 v70, v18, v19
	v_cvt_pk_bf16_f32 v71, v16, v17
	v_pk_fma_f32 v[10:11], v[10:11], v[86:87], v[72:73]
	v_cvt_pk_bf16_f32 v72, v12, v13
	v_pk_mul_f32 v[14:15], v[78:79], v[16:17]
	v_cvt_pk_bf16_f32 v73, v10, v11
	global_store_dwordx4 v69, v[70:73], s[8:9] nt
	v_add_u32_e32 v69, v140, v156
	v_pk_mul_f32 v[74:75], v[82:83], v[10:11]
	v_pk_mul_f32 v[70:71], v[76:77], v[18:19]
	v_pk_mul_f32 v[72:73], v[80:81], v[12:13]
	v_cvt_pk_bf16_f32 v70, v70, v71
	v_cvt_pk_bf16_f32 v71, v14, v15
	ds_swizzle_b32 v14, v68 offset:swizzle(SWAP,16)
	v_cvt_pk_bf16_f32 v72, v72, v73
	v_cvt_pk_bf16_f32 v73, v74, v75
	global_store_dwordx4 v69, v[70:73], s[18:19] nt
	s_waitcnt lgkmcnt(0)
	v_add_f32_e32 v14, v68, v14
	v_mov_b32_e32 v15, v14
	s_nop 1
	v_permlane32_swap_b32_e32 v14, v15
	s_and_saveexec_b64 s[30:31], vcc
	s_cbranch_execz .LBB13_1928
	s_lshl_b32 s29, s12, 14
	s_lshl_b32 s38, s27, 2
	s_add_i32 s38, s38, s29
	v_add_f32_e32 v14, v14, v15
	v_lshl_add_u32 v15, v9, 6, s38
	global_store_dword v15, v14, s[20:21]
